# speedup vs baseline: 1.0732x; 1.0078x over previous
; DI int tid_opaque() { int t = threadIdx.x; asm volatile("" : "+v"(t)); return t; }
; DI void dma_stage(const bf16_t* __restrict__ A, int lda, const bf16_t* __restrict__ B, int ldb, int k0, char* stage, int w, int lane) {
;   const int lr = lane >> 2, pos = lane & 3;
;   _Pragma("unroll") for (int i = 0; i < 4; ++i) {
;     const int idx = w + 8 * i;
;     const int row = (idx << 4) + lr;
;     const int c = pos ^ ((row >> 2) & 3);
;     const bf16_t* g = (i < 2) ? (A + (size_t)row * lda + k0 + c * 8) : (B + (size_t)(row - 256) * ldb + k0 + c * 8);
;     __builtin_amdgcn_global_load_lds((const unsigned*)g, (unsigned*)(stage + idx * 1024 + lane * 16), 16, 0, 0);
;   }
; }
; DI void gemm_mainloop(const bf16_t* __restrict__ A, int lda, const bf16_t* __restrict__ B, int ldb, int K,
;                       f32x16 (&acc)[2][4], char* smem, const int tid) {
;   const int lane = tid & 63, w = tid >> 6;
;   const int wm = w >> 1, wn = w & 1, r = lane & 31, h = lane >> 5;
;   const int swz = (r >> 2) & 3;
;   const int o0 = ((0 + h) ^ swz) << 4, o1 = ((2 + h) ^ swz) << 4;
;   const int aoff = (wm * 64 + r) * 64, boff = (256 + wn * 128 + r) * 64;
;   const int nk = K >> 5;
;   dma_stage(A, lda, B, ldb, 0, smem, w, lane);
;   dma_stage(A, lda, B, ldb, 32, smem + STG, w, lane);
;   dma_stage(A, lda, B, ldb, 64, smem + 2 * STG, w, lane);
; DI void p1_tile(const Params& P, int l, int half, int t, char* smem) {
;   int tm, tn; tile_decode(t, 44, tm, tn);
;   const int m0 = tm * 256, n0 = tn * 256;
;   const int tid = tid_opaque(), lane = tid & 63, w = tid >> 6, wm = w >> 1, wn = w & 1, r = lane & 31, h = lane >> 5;
;   f32x16 acc[2][4]; zero_acc(acc);
;   const float rsum = rstd_prefetch<32>(P.sq_x + ((size_t)half * TH + m0) * 32, tid);
;   gemm_mainloop(P.xb + ((size_t)half * TH + m0) * DM, DM, P.wt_in + ((size_t)l * NINP + n0) * DM, DM, DM, acc, smem, tid);
.LBB0_237:
	s_or_b64 exec, exec, s[0:1]
	v_ashrrev_i32_e32 v197, 1, v128
	v_and_b32_e32 v198, 31, v128
	v_and_b32_e32 v134, 0xffffffc0, v197
	v_ashrrev_i32_e32 v154, 6, v128
	v_or_b32_e32 v0, v134, v198
	s_mul_i32 s4, s2, 0xfffffea0
	v_lshlrev_b32_e32 v156, 6, v0
	v_lshlrev_b32_e32 v0, 7, v154
	s_add_i32 s4, s4, s69
	v_and_b32_e32 v155, 0x80, v0
	s_lshl_b32 s70, s4, 5
	v_readlane_b32 s36, v249, 18
	v_or_b32_e32 v0, v155, v198
	s_and_b32 s5, s93, 0x700
	s_and_b32 s0, s70, 0xffffff00
	v_and_b32_e32 v129, 63, v128
	s_lshl_b64 s[6:7], s[28:29], 12
	v_readlane_b32 s50, v249, 32
	v_lshlrev_b32_e32 v157, 6, v0
	v_bfe_u32 v12, v128, 2, 4
	v_bfe_u32 v0, v128, 4, 2
	v_add_u32_e32 v13, 8, v154
	v_readlane_b32 s51, v249, 33
	s_add_u32 s6, s50, s6
	v_bitop3_b32 v0, v0, v128, 3 bitop3:0x78
	v_lshlrev_b32_e32 v16, 4, v129
	v_lshl_or_b32 v4, v154, 4, v12
	v_lshl_or_b32 v10, v13, 4, v12
	s_addc_u32 s7, s51, s7
	s_ashr_i32 s1, s0, 31
	v_add_u32_e32 v158, 0, v16
	v_lshlrev_b32_e32 v132, 4, v0
	v_ashrrev_i32_e32 v5, 31, v4
	v_lshlrev_b32_e32 v159, 10, v154
	v_ashrrev_i32_e32 v11, 31, v10
	s_lshl_b64 s[8:9], s[0:1], 12
	v_lshl_add_u64 v[2:3], s[6:7], 0, v[132:133]
	v_lshlrev_b64 v[6:7], 12, v[4:5]
	v_add_u32_e32 v5, v158, v159
	v_lshlrev_b64 v[10:11], 12, v[10:11]
	v_lshlrev_b32_e32 v160, 10, v13
	v_add_u32_e32 v13, 16, v154
	v_or_b32_e32 v12, 0xffffff00, v12
	s_add_u32 s8, s90, s8
	v_lshl_add_u64 v[8:9], v[2:3], 0, v[6:7]
	v_readfirstlane_b32 s1, v5
	v_lshl_add_u64 v[2:3], v[2:3], 0, v[10:11]
	v_add_u32_e32 v17, v158, v160
	v_lshl_add_u32 v10, v13, 4, v12
	v_lshlrev_b32_e32 v161, 10, v13
	v_add_u32_e32 v19, 24, v154
	s_addc_u32 s9, s91, s9
	s_mov_b32 m0, s1
	v_readfirstlane_b32 s1, v17
	v_ashrrev_i32_e32 v11, 31, v10
	v_add_u32_e32 v18, v158, v161
	v_lshl_add_u32 v12, v19, 4, v12
	v_lshlrev_b32_e32 v162, 10, v19
	v_lshl_add_u64 v[0:1], s[8:9], 0, v[132:133]
	global_load_lds_dwordx4 v[8:9], off
	s_mov_b32 m0, s1
	v_lshlrev_b64 v[10:11], 12, v[10:11]
	v_readfirstlane_b32 s1, v18
	v_ashrrev_i32_e32 v13, 31, v12
	v_add_u32_e32 v19, v158, v162
	global_load_lds_dwordx4 v[2:3], off
	v_lshl_add_u64 v[10:11], v[0:1], 0, v[10:11]
	s_mov_b32 m0, s1
	v_lshlrev_b64 v[12:13], 12, v[12:13]
	v_readfirstlane_b32 s1, v19
	v_add_u32_e32 v5, 0x8000, v5
	global_load_lds_dwordx4 v[10:11], off
	v_lshl_add_u64 v[0:1], v[0:1], 0, v[12:13]
	s_mov_b32 m0, s1
	v_readfirstlane_b32 s1, v5
	v_add_u32_e32 v5, 0x8000, v17
	global_load_lds_dwordx4 v[0:1], off
	v_lshl_add_u64 v[12:13], v[8:9], 0, 64
	s_mov_b32 m0, s1
	v_readfirstlane_b32 s1, v5
	v_add_u32_e32 v5, 0x8000, v18
	global_load_lds_dwordx4 v[12:13], off
	v_lshl_add_u64 v[12:13], v[2:3], 0, 64
	s_mov_b32 m0, s1
	v_readfirstlane_b32 s1, v5
	v_add_u32_e32 v5, 0x8000, v19
	global_load_lds_dwordx4 v[12:13], off
	v_lshl_add_u64 v[12:13], v[10:11], 0, 64
	s_mov_b32 m0, s1
	v_readfirstlane_b32 s1, v5
	global_load_lds_dwordx4 v[12:13], off
	v_lshl_add_u64 v[12:13], v[0:1], 0, 64
	s_mov_b32 m0, s1
	v_add_u32_e32 v5, s64, v16
	global_load_lds_dwordx4 v[12:13], off
	v_add_u32_e32 v12, v5, v159
	v_lshl_add_u64 v[8:9], v[8:9], 0, s[94:95]
	v_readfirstlane_b32 s1, v12
	s_mov_b32 m0, s1
	v_lshl_add_u64 v[2:3], v[2:3], 0, s[94:95]
	global_load_lds_dwordx4 v[8:9], off
	v_add_u32_e32 v8, v5, v160
	v_lshl_add_u64 v[0:1], v[0:1], 0, s[94:95]
	v_readfirstlane_b32 s1, v8
	v_add_u32_e32 v8, v5, v161
	s_mov_b32 m0, s1
	v_readfirstlane_b32 s1, v8
	global_load_lds_dwordx4 v[2:3], off
	v_lshl_add_u64 v[2:3], v[10:11], 0, s[94:95]
	s_mov_b32 m0, s1
	v_bfe_u32 v199, v128, 5, 1
	global_load_lds_dwordx4 v[2:3], off
	v_add_u32_e32 v2, v5, v162
	v_lshrrev_b32_e32 v14, 2, v128
	v_readfirstlane_b32 s1, v2
	s_mov_b32 m0, s1
	v_bfe_u32 v15, v128, 2, 2
	global_load_lds_dwordx4 v[0:1], off
	v_bitop3_b32 v0, v199, v14, 3 bitop3:0x78
	s_mulk_i32 s2, 0x2c00
	v_lshlrev_b32_e32 v163, 4, v0
	v_bitop3_b32 v0, v199, v15, 2 bitop3:0x36
	s_sub_i32 s1, s62, s2
	v_lshlrev_b32_e32 v164, 4, v0
	v_add_u32_e32 v0, 0x80, v4
	s_add_i32 s30, s3, s5
	s_and_b32 s2, s1, 0xffffff00
	v_ashrrev_i32_e32 v1, 31, v0
	s_ashr_i32 s31, s30, 31
	s_ashr_i32 s3, s2, 31
	v_lshlrev_b64 v[0:1], 12, v[0:1]
	s_lshl_b64 s[6:7], s[30:31], 12
	s_lshl_b64 s[2:3], s[2:3], 12
	v_lshl_add_u64 v[2:3], v[0:1], 0, s[6:7]
	v_lshl_add_u64 v[0:1], s[2:3], 0, v[0:1]
	v_or_b32_e32 v0, v0, v132
	v_or_b32_e32 v2, v2, v132
	v_lshl_add_u64 v[138:139], s[90:91], 0, v[0:1]
	v_lshl_add_u64 v[0:1], s[2:3], 0, v[6:7]
	v_lshl_add_u64 v[130:131], s[50:51], 0, v[2:3]
	v_lshl_add_u64 v[2:3], s[6:7], 0, v[6:7]
	v_or_b32_e32 v0, v0, v132
	v_or_b32_e32 v2, v2, v132
	v_lshl_add_u64 v[140:141], s[90:91], 0, v[0:1]
	v_mov_b32_e32 v0, 0
	v_lshl_add_u64 v[136:137], s[50:51], 0, v[2:3]
	s_mov_b64 s[2:3], 0
	s_mov_b32 s1, 0
	v_mov_b32_e32 v1, v0
	v_mov_b32_e32 v2, v0
	v_mov_b32_e32 v3, v0
	v_mov_b32_e32 v4, v0
	v_mov_b32_e32 v5, v0
	v_mov_b32_e32 v6, v0
	v_mov_b32_e32 v7, v0
	v_mov_b32_e32 v8, v0
	v_mov_b32_e32 v9, v0
	v_mov_b32_e32 v10, v0
	v_mov_b32_e32 v11, v0
	v_mov_b32_e32 v12, v0
	v_mov_b32_e32 v13, v0
	v_mov_b32_e32 v14, v0
	v_mov_b32_e32 v15, v0
	v_mov_b32_e32 v16, v0
	v_mov_b32_e32 v17, v0
	v_mov_b32_e32 v18, v0
	v_mov_b32_e32 v19, v0
	v_mov_b32_e32 v20, v0
	v_mov_b32_e32 v21, v0
	v_mov_b32_e32 v22, v0
	v_mov_b32_e32 v23, v0
	v_mov_b32_e32 v24, v0
	v_mov_b32_e32 v25, v0
	v_mov_b32_e32 v26, v0
	v_mov_b32_e32 v27, v0
	v_mov_b32_e32 v28, v0
	v_mov_b32_e32 v29, v0
	v_mov_b32_e32 v30, v0
	v_mov_b32_e32 v31, v0
	v_mov_b32_e32 v64, v0
	v_mov_b32_e32 v65, v0
	v_mov_b32_e32 v66, v0
	v_mov_b32_e32 v67, v0
	v_mov_b32_e32 v68, v0
	v_mov_b32_e32 v69, v0
	v_mov_b32_e32 v70, v0
	v_mov_b32_e32 v71, v0
	v_mov_b32_e32 v72, v0
	v_mov_b32_e32 v73, v0
; DI void gemm_mainloop(const bf16_t* __restrict__ A, int lda, const bf16_t* __restrict__ B, int ldb, int K,
;                       f32x16 (&acc)[2][4], char* smem, const int tid) {
;     ...
;   for (int kt = 0; kt < nk; ++kt) {
;     asm volatile("s_waitcnt vmcnt(8) lgkmcnt(0)" ::: "memory");
;     __builtin_amdgcn_s_barrier();
;     dma_stage(A, lda, B, ldb, (kt + 3) * 32, smem + ((kt + 3) & 3) * STG, w, lane);
;     const char* st = smem + (kt & 3) * STG;
;     _Pragma("unroll") for (int ks = 0; ks < 2; ++ks) {
;       const int oo = ks ? o1 : o0;
;       bf16x8 a0 = *(const bf16x8*)(st + aoff + oo);
;       bf16x8 a1 = *(const bf16x8*)(st + aoff + 32 * 64 + oo);
;       bf16x8 b0 = *(const bf16x8*)(st + boff + oo);
;       bf16x8 b1 = *(const bf16x8*)(st + boff + 32 * 64 + oo);
;       bf16x8 b2 = *(const bf16x8*)(st + boff + 64 * 64 + oo);
;       bf16x8 b3 = *(const bf16x8*)(st + boff + 96 * 64 + oo);
; DI void p1_tile(const Params& P, int l, int half, int t, char* smem) {
;     ...
;   f32x16 acc[2][4]; zero_acc(acc);
	v_mov_b32_e32 v74, v0
	v_mov_b32_e32 v75, v0
	v_mov_b32_e32 v76, v0
	v_mov_b32_e32 v77, v0
	v_mov_b32_e32 v78, v0
	v_mov_b32_e32 v79, v0
	v_mov_b32_e32 v80, v0
	v_mov_b32_e32 v81, v0
	v_mov_b32_e32 v82, v0
	v_mov_b32_e32 v83, v0
	v_mov_b32_e32 v84, v0
	v_mov_b32_e32 v85, v0
	v_mov_b32_e32 v86, v0
	v_mov_b32_e32 v87, v0
	v_mov_b32_e32 v88, v0
	v_mov_b32_e32 v89, v0
	v_mov_b32_e32 v90, v0
	v_mov_b32_e32 v91, v0
	v_mov_b32_e32 v92, v0
	v_mov_b32_e32 v93, v0
	v_mov_b32_e32 v94, v0
	v_mov_b32_e32 v95, v0
	v_mov_b32_e32 v32, v0
	v_mov_b32_e32 v33, v0
	v_mov_b32_e32 v34, v0
	v_mov_b32_e32 v35, v0
	v_mov_b32_e32 v36, v0
	v_mov_b32_e32 v37, v0
	v_mov_b32_e32 v38, v0
	v_mov_b32_e32 v39, v0
	v_mov_b32_e32 v40, v0
	v_mov_b32_e32 v41, v0
	v_mov_b32_e32 v42, v0
	v_mov_b32_e32 v43, v0
	v_mov_b32_e32 v44, v0
	v_mov_b32_e32 v45, v0
	v_mov_b32_e32 v46, v0
	v_mov_b32_e32 v47, v0
	v_mov_b32_e32 v48, v0
	v_mov_b32_e32 v49, v0
	v_mov_b32_e32 v50, v0
	v_mov_b32_e32 v51, v0
	v_mov_b32_e32 v52, v0
	v_mov_b32_e32 v53, v0
	v_mov_b32_e32 v54, v0
	v_mov_b32_e32 v55, v0
	v_mov_b32_e32 v56, v0
	v_mov_b32_e32 v57, v0
	v_mov_b32_e32 v58, v0
	v_mov_b32_e32 v59, v0
	v_mov_b32_e32 v60, v0
	v_mov_b32_e32 v61, v0
	v_mov_b32_e32 v62, v0
	v_mov_b32_e32 v63, v0
	v_mov_b32_e32 v96, v0
	v_mov_b32_e32 v97, v0
	v_mov_b32_e32 v98, v0
	v_mov_b32_e32 v99, v0
	v_mov_b32_e32 v100, v0
	v_mov_b32_e32 v101, v0
	v_mov_b32_e32 v102, v0
	v_mov_b32_e32 v103, v0
	v_mov_b32_e32 v104, v0
	v_mov_b32_e32 v105, v0
	v_mov_b32_e32 v106, v0
	v_mov_b32_e32 v107, v0
	v_mov_b32_e32 v108, v0
	v_mov_b32_e32 v109, v0
	v_mov_b32_e32 v110, v0
	v_mov_b32_e32 v111, v0
	v_mov_b32_e32 v112, v0
	v_mov_b32_e32 v113, v0
	v_mov_b32_e32 v114, v0
	v_mov_b32_e32 v115, v0
	v_mov_b32_e32 v116, v0
	v_mov_b32_e32 v117, v0
	v_mov_b32_e32 v118, v0
	v_mov_b32_e32 v119, v0
	v_mov_b32_e32 v120, v0
	v_mov_b32_e32 v121, v0
	v_mov_b32_e32 v122, v0
	v_mov_b32_e32 v123, v0
	v_mov_b32_e32 v124, v0
	v_mov_b32_e32 v125, v0
	v_mov_b32_e32 v126, v0
	v_mov_b32_e32 v127, v0
	v_readlane_b32 s37, v249, 19
	v_readlane_b32 s38, v249, 20
	v_readlane_b32 s39, v249, 21
	v_readlane_b32 s40, v249, 22
	v_readlane_b32 s41, v249, 23
	v_readlane_b32 s42, v249, 24
	v_readlane_b32 s43, v249, 25
	v_readlane_b32 s44, v249, 26
	v_readlane_b32 s45, v249, 27
	v_readlane_b32 s46, v249, 28
	v_readlane_b32 s47, v249, 29
	v_readlane_b32 s48, v249, 30
	v_readlane_b32 s49, v249, 31
	v_add_u32_e32 v205, v158, v159
	v_add_u32_e32 v190, v156, v163
	v_add_u32_e32 v191, v157, v163
	v_readfirstlane_b32 s5, v205
	v_add_u32_e32 v132, v156, v164
	v_add_u32_e32 v165, v157, v164
	s_waitcnt vmcnt(8) lgkmcnt(0)
	s_barrier
	ds_read_b128 v[166:169], v190
	ds_read_b128 v[170:173], v190 offset:2048
	ds_read_b128 v[174:177], v191 offset:16384
	ds_read_b128 v[178:181], v191 offset:18432
	ds_read_b128 v[182:185], v191 offset:20480
	ds_read_b128 v[186:189], v191 offset:22528
	ds_read_b128 v[212:215], v132
	ds_read_b128 v[216:219], v132 offset:2048
	ds_read_b128 v[220:223], v165 offset:16384
	ds_read_b128 v[224:227], v165 offset:18432
	ds_read_b128 v[228:231], v165 offset:20480
	ds_read_b128 v[232:235], v165 offset:22528
	s_add_u32 m0, s5, 0x18000
	v_lshl_add_u64 v[142:143], v[136:137], 0, s[20:21]
	v_lshl_add_u64 v[148:149], v[130:131], 0, s[20:21]
	global_load_lds_dwordx4 v[142:143], off
	s_add_u32 m0, s5, 0x1a000
	v_lshl_add_u64 v[142:143], v[140:141], 0, s[20:21]
	global_load_lds_dwordx4 v[148:149], off
	s_add_u32 m0, s5, 0x1c000
	v_lshl_add_u64 v[148:149], v[138:139], 0, s[20:21]
	global_load_lds_dwordx4 v[142:143], off
	s_add_u32 m0, s5, 0x1e000
	s_add_u32 s20, s20, 64
	global_load_lds_dwordx4 v[148:149], off
	s_addc_u32 s21, s21, 0
; #define MFMA32(a, b, c) __builtin_amdgcn_mfma_f32_32x32x16_bf16((a), (b), (c), 0, 0, 0)
; DI void gemm_mainloop(const bf16_t* __restrict__ A, int lda, const bf16_t* __restrict__ B, int ldb, int K,
;                       f32x16 (&acc)[2][4], char* smem, const int tid) {
;     ...
;   for (int kt = 0; kt < nk; ++kt) {
;     asm volatile("s_waitcnt vmcnt(8) lgkmcnt(0)" ::: "memory");
;     __builtin_amdgcn_s_barrier();
;     dma_stage(A, lda, B, ldb, (kt + 3) * 32, smem + ((kt + 3) & 3) * STG, w, lane);
;     const char* st = smem + (kt & 3) * STG;
;     _Pragma("unroll") for (int ks = 0; ks < 2; ++ks) {
;       const int oo = ks ? o1 : o0;
;       bf16x8 a0 = *(const bf16x8*)(st + aoff + oo);
;       bf16x8 a1 = *(const bf16x8*)(st + aoff + 32 * 64 + oo);
;       bf16x8 b0 = *(const bf16x8*)(st + boff + oo);
;       bf16x8 b1 = *(const bf16x8*)(st + boff + 32 * 64 + oo);
;       bf16x8 b2 = *(const bf16x8*)(st + boff + 64 * 64 + oo);
;       bf16x8 b3 = *(const bf16x8*)(st + boff + 96 * 64 + oo);
;       acc[0][0] = MFMA32(a0, b0, acc[0][0]); acc[0][1] = MFMA32(a0, b1, acc[0][1]);
;       acc[0][2] = MFMA32(a0, b2, acc[0][2]); acc[0][3] = MFMA32(a0, b3, acc[0][3]);
;       acc[1][0] = MFMA32(a1, b0, acc[1][0]); acc[1][1] = MFMA32(a1, b1, acc[1][1]);
;       acc[1][2] = MFMA32(a1, b2, acc[1][2]); acc[1][3] = MFMA32(a1, b3, acc[1][3]);
;     }
;   }
;   asm volatile("s_waitcnt vmcnt(0)" ::: "memory");
;   __syncthreads();
.Lgm_p1p_loop:
	s_waitcnt lgkmcnt(6)
	v_mfma_f32_32x32x16_bf16 v[112:127], v[166:169], v[174:177], v[112:127]
	v_mfma_f32_32x32x16_bf16 v[96:111], v[166:169], v[178:181], v[96:111]
	v_mfma_f32_32x32x16_bf16 v[48:63], v[166:169], v[182:185], v[48:63]
	v_mfma_f32_32x32x16_bf16 v[32:47], v[166:169], v[186:189], v[32:47]
	v_mfma_f32_32x32x16_bf16 v[80:95], v[170:173], v[174:177], v[80:95]
	v_mfma_f32_32x32x16_bf16 v[64:79], v[170:173], v[178:181], v[64:79]
	v_mfma_f32_32x32x16_bf16 v[16:31], v[170:173], v[182:185], v[16:31]
	v_mfma_f32_32x32x16_bf16 v[0:15], v[170:173], v[186:189], v[0:15]
	s_waitcnt vmcnt(8) lgkmcnt(0)
	s_barrier
	ds_read_b128 v[166:169], v190 offset:32768
	ds_read_b128 v[170:173], v190 offset:34816
	ds_read_b128 v[174:177], v191 offset:49152
	ds_read_b128 v[178:181], v191 offset:51200
	ds_read_b128 v[182:185], v191 offset:53248
	ds_read_b128 v[186:189], v191 offset:55296
	v_mfma_f32_32x32x16_bf16 v[112:127], v[212:215], v[220:223], v[112:127]
	s_mov_b32 m0, s5
	v_lshl_add_u64 v[142:143], v[136:137], 0, s[20:21]
	v_mfma_f32_32x32x16_bf16 v[96:111], v[212:215], v[224:227], v[96:111]
	global_load_lds_dwordx4 v[142:143], off
	s_add_u32 m0, s5, 0x2000
	v_lshl_add_u64 v[148:149], v[130:131], 0, s[20:21]
	v_mfma_f32_32x32x16_bf16 v[48:63], v[212:215], v[228:231], v[48:63]
	global_load_lds_dwordx4 v[148:149], off
	s_add_u32 m0, s5, 0x4000
	v_lshl_add_u64 v[142:143], v[140:141], 0, s[20:21]
	v_mfma_f32_32x32x16_bf16 v[32:47], v[212:215], v[232:235], v[32:47]
	global_load_lds_dwordx4 v[142:143], off
	s_add_u32 m0, s5, 0x6000
	v_lshl_add_u64 v[148:149], v[138:139], 0, s[20:21]
	v_mfma_f32_32x32x16_bf16 v[80:95], v[216:219], v[220:223], v[80:95]
	global_load_lds_dwordx4 v[148:149], off
	s_add_u32 s20, s20, 64
	s_addc_u32 s21, s21, 0
	v_mfma_f32_32x32x16_bf16 v[64:79], v[216:219], v[224:227], v[64:79]
	v_mfma_f32_32x32x16_bf16 v[16:31], v[216:219], v[228:231], v[16:31]
	v_mfma_f32_32x32x16_bf16 v[0:15], v[216:219], v[232:235], v[0:15]
	ds_read_b128 v[212:215], v132 offset:32768
	ds_read_b128 v[216:219], v132 offset:34816
	ds_read_b128 v[220:223], v165 offset:49152
	ds_read_b128 v[224:227], v165 offset:51200
	ds_read_b128 v[228:231], v165 offset:53248
	ds_read_b128 v[232:235], v165 offset:55296
	v_xor_b32_e32 v190, 0x10000, v190
	v_xor_b32_e32 v191, 0x10000, v191
	v_xor_b32_e32 v132, 0x10000, v132
	v_xor_b32_e32 v165, 0x10000, v165
	s_waitcnt lgkmcnt(6)
	v_mfma_f32_32x32x16_bf16 v[112:127], v[166:169], v[174:177], v[112:127]
	v_mfma_f32_32x32x16_bf16 v[96:111], v[166:169], v[178:181], v[96:111]
	v_mfma_f32_32x32x16_bf16 v[48:63], v[166:169], v[182:185], v[48:63]
	v_mfma_f32_32x32x16_bf16 v[32:47], v[166:169], v[186:189], v[32:47]
	v_mfma_f32_32x32x16_bf16 v[80:95], v[170:173], v[174:177], v[80:95]
	v_mfma_f32_32x32x16_bf16 v[64:79], v[170:173], v[178:181], v[64:79]
	v_mfma_f32_32x32x16_bf16 v[16:31], v[170:173], v[182:185], v[16:31]
	v_mfma_f32_32x32x16_bf16 v[0:15], v[170:173], v[186:189], v[0:15]
	s_waitcnt vmcnt(8) lgkmcnt(0)
	s_barrier
	ds_read_b128 v[166:169], v190
	ds_read_b128 v[170:173], v190 offset:2048
	ds_read_b128 v[174:177], v191 offset:16384
	ds_read_b128 v[178:181], v191 offset:18432
	ds_read_b128 v[182:185], v191 offset:20480
	ds_read_b128 v[186:189], v191 offset:22528
	v_mfma_f32_32x32x16_bf16 v[112:127], v[212:215], v[220:223], v[112:127]
	s_add_u32 m0, s5, 0x8000
	v_lshl_add_u64 v[142:143], v[136:137], 0, s[20:21]
	v_mfma_f32_32x32x16_bf16 v[96:111], v[212:215], v[224:227], v[96:111]
	global_load_lds_dwordx4 v[142:143], off
	s_add_u32 m0, s5, 0xa000
	v_lshl_add_u64 v[148:149], v[130:131], 0, s[20:21]
	v_mfma_f32_32x32x16_bf16 v[48:63], v[212:215], v[228:231], v[48:63]
	global_load_lds_dwordx4 v[148:149], off
	s_add_u32 m0, s5, 0xc000
	v_lshl_add_u64 v[142:143], v[140:141], 0, s[20:21]
	v_mfma_f32_32x32x16_bf16 v[32:47], v[212:215], v[232:235], v[32:47]
	global_load_lds_dwordx4 v[142:143], off
	s_add_u32 m0, s5, 0xe000
	v_lshl_add_u64 v[148:149], v[138:139], 0, s[20:21]
	v_mfma_f32_32x32x16_bf16 v[80:95], v[216:219], v[220:223], v[80:95]
	global_load_lds_dwordx4 v[148:149], off
	s_add_u32 s20, s20, 64
	s_addc_u32 s21, s21, 0
	v_mfma_f32_32x32x16_bf16 v[64:79], v[216:219], v[224:227], v[64:79]
	v_mfma_f32_32x32x16_bf16 v[16:31], v[216:219], v[228:231], v[16:31]
	v_mfma_f32_32x32x16_bf16 v[0:15], v[216:219], v[232:235], v[0:15]
	ds_read_b128 v[212:215], v132
	ds_read_b128 v[216:219], v132 offset:2048
	ds_read_b128 v[220:223], v165 offset:16384
	ds_read_b128 v[224:227], v165 offset:18432
	ds_read_b128 v[228:231], v165 offset:20480
	ds_read_b128 v[232:235], v165 offset:22528
	s_xor_b32 s5, s5, 0x10000
	s_add_u32 s2, s2, 0x80
	s_cmpk_lg_i32 s2, 0x1000
	s_cbranch_scc1 .Lgm_p1p_loop
	s_waitcnt lgkmcnt(0)
	s_mov_b64 s[20:21], 0xc0
	s_waitcnt vmcnt(0)
	s_waitcnt vmcnt(0)
	s_barrier
	s_and_saveexec_b64 s[2:3], vcc
	s_cbranch_execz .LBB0_241
	v_mul_f32_e32 v130, 0x4b800000, v135
	v_cmp_gt_f32_e32 vcc, s24, v135
	v_lshl_add_u32 v131, v128, 2, 0
	v_add_u32_e32 v131, 0x12000, v131
	v_cndmask_b32_e32 v130, v135, v130, vcc
	v_rsq_f32_e32 v130, v130
	s_nop 0
	v_mul_f32_e32 v132, 0x45800000, v130
	v_cndmask_b32_e32 v130, v130, v132, vcc
	ds_write_b32 v131, v130

; DI int tid_opaque() { int t = threadIdx.x; asm volatile("" : "+v"(t)); return t; }
; DI void dma_stage(const bf16_t* __restrict__ A, int lda, const bf16_t* __restrict__ B, int ldb, int k0, char* stage, int w, int lane) {
;   const int lr = lane >> 2, pos = lane & 3;
;   _Pragma("unroll") for (int i = 0; i < 4; ++i) {
;     const int idx = w + 8 * i;
;     const int row = (idx << 4) + lr;
;     const int c = pos ^ ((row >> 2) & 3);
;     const bf16_t* g = (i < 2) ? (A + (size_t)row * lda + k0 + c * 8) : (B + (size_t)(row - 256) * ldb + k0 + c * 8);
;     __builtin_amdgcn_global_load_lds((const unsigned*)g, (unsigned*)(stage + idx * 1024 + lane * 16), 16, 0, 0);
;   }
; }
; DI void gemm_mainloop(const bf16_t* __restrict__ A, int lda, const bf16_t* __restrict__ B, int ldb, int K,
;                       f32x16 (&acc)[2][4], char* smem, const int tid) {
;   const int lane = tid & 63, w = tid >> 6;
;   const int wm = w >> 1, wn = w & 1, r = lane & 31, h = lane >> 5;
;   const int swz = (r >> 2) & 3;
;   const int o0 = ((0 + h) ^ swz) << 4, o1 = ((2 + h) ^ swz) << 4;
;   const int aoff = (wm * 64 + r) * 64, boff = (256 + wn * 128 + r) * 64;
;   const int nk = K >> 5;
;   dma_stage(A, lda, B, ldb, 0, smem, w, lane);
;   dma_stage(A, lda, B, ldb, 32, smem + STG, w, lane);
;   dma_stage(A, lda, B, ldb, 64, smem + 2 * STG, w, lane);
; DI void p1_tile(const Params& P, int l, int half, int t, char* smem) {
;   int tm, tn; tile_decode(t, 44, tm, tn);
;   const int m0 = tm * 256, n0 = tn * 256;
;   const int tid = tid_opaque(), lane = tid & 63, w = tid >> 6, wm = w >> 1, wn = w & 1, r = lane & 31, h = lane >> 5;
;   f32x16 acc[2][4]; zero_acc(acc);
;   const float rsum = rstd_prefetch<32>(P.sq_x + ((size_t)half * TH + m0) * 32, tid);
;   gemm_mainloop(P.xb + ((size_t)half * TH + m0) * DM, DM, P.wt_in + ((size_t)l * NINP + n0) * DM, DM, DM, acc, smem, tid);
.LBB0_660:
	s_ashr_i32 s0, s21, 31
	s_lshr_b32 s0, s0, 26
	s_add_i32 s0, s21, s0
	s_lshl_b32 s0, s0, 5
	v_mov_b32_e32 v157, v144
	s_and_b32 s24, s0, 0xfffff800
	s_lshl_b32 s0, s21, 8
	s_and_b32 s0, s0, 0x700
	v_ashrrev_i32_e32 v0, 1, v157
	s_lshl_b32 s1, s21, 5
	v_and_b32_e32 v156, 31, v157
	v_and_b32_e32 v155, 0xffffffc0, v0
	s_or_b32 s0, s24, s0
	s_sub_i32 s1, s1, s24
	v_ashrrev_i32_e32 v159, 6, v157
	v_or_b32_e32 v0, v155, v156
	s_and_b32 s16, s1, 0xffffff00
	s_ashr_i32 s1, s0, 31
	v_lshlrev_b32_e32 v161, 6, v0
	v_lshlrev_b32_e32 v0, 7, v159
	s_and_b32 s17, s20, 0x700
	s_lshl_b64 s[2:3], s[0:1], 12
	v_and_b32_e32 v160, 0x80, v0
	s_add_u32 s2, s60, s2
	v_or_b32_e32 v0, v160, v156
	v_and_b32_e32 v154, 63, v157
	s_addc_u32 s3, s61, s3
	s_ashr_i32 s1, s16, 31
	v_lshlrev_b32_e32 v162, 6, v0
	v_bfe_u32 v12, v157, 2, 4
	v_bfe_u32 v0, v157, 4, 2
	v_add_u32_e32 v13, 8, v159
	s_add_u32 s22, s16, s18
	v_bitop3_b32 v0, v0, v157, 3 bitop3:0x78
	v_lshlrev_b32_e32 v16, 4, v154
	v_lshl_or_b32 v4, v159, 4, v12
	v_lshl_or_b32 v10, v13, 4, v12
	s_addc_u32 s23, s1, 0
	v_add_u32_e32 v163, 0, v16
	v_lshlrev_b32_e32 v152, 4, v0
	v_ashrrev_i32_e32 v5, 31, v4
	v_lshlrev_b32_e32 v164, 10, v159
	v_ashrrev_i32_e32 v11, 31, v10
	s_lshl_b64 s[22:23], s[22:23], 12
	v_lshl_add_u64 v[2:3], s[2:3], 0, v[152:153]
	v_lshlrev_b64 v[6:7], 12, v[4:5]
	v_add_u32_e32 v5, v163, v164
	v_lshlrev_b64 v[10:11], 12, v[10:11]
	v_lshlrev_b32_e32 v165, 10, v13
	v_add_u32_e32 v13, 16, v159
	v_or_b32_e32 v12, 0xffffff00, v12
	s_add_u32 s22, s48, s22
	v_lshl_add_u64 v[8:9], v[2:3], 0, v[6:7]
	v_readfirstlane_b32 s1, v5
	v_lshl_add_u64 v[2:3], v[2:3], 0, v[10:11]
	v_add_u32_e32 v17, v163, v165
	v_lshl_add_u32 v10, v13, 4, v12
	v_lshlrev_b32_e32 v166, 10, v13
	v_add_u32_e32 v19, 24, v159
	s_addc_u32 s23, s49, s23
	s_mov_b32 m0, s1
	v_readfirstlane_b32 s1, v17
	v_ashrrev_i32_e32 v11, 31, v10
	v_add_u32_e32 v18, v163, v166
	v_lshl_add_u32 v12, v19, 4, v12
	v_lshlrev_b32_e32 v167, 10, v19
	v_lshl_add_u64 v[0:1], s[22:23], 0, v[152:153]
	global_load_lds_dwordx4 v[8:9], off
	s_mov_b32 m0, s1
	v_lshlrev_b64 v[10:11], 12, v[10:11]
	v_readfirstlane_b32 s1, v18
	v_ashrrev_i32_e32 v13, 31, v12
	v_add_u32_e32 v19, v163, v167
	global_load_lds_dwordx4 v[2:3], off
	v_lshl_add_u64 v[10:11], v[0:1], 0, v[10:11]
	s_mov_b32 m0, s1
	v_lshlrev_b64 v[12:13], 12, v[12:13]
	v_readfirstlane_b32 s1, v19
	v_add_u32_e32 v5, 0x8000, v5
	global_load_lds_dwordx4 v[10:11], off
	v_lshl_add_u64 v[0:1], v[0:1], 0, v[12:13]
	s_mov_b32 m0, s1
	v_readfirstlane_b32 s1, v5
	v_add_u32_e32 v5, 0x8000, v17
	global_load_lds_dwordx4 v[0:1], off
	v_lshl_add_u64 v[12:13], v[8:9], 0, 64
	s_mov_b32 m0, s1
	v_readfirstlane_b32 s1, v5
	v_add_u32_e32 v5, 0x8000, v18
	global_load_lds_dwordx4 v[12:13], off
	v_lshl_add_u64 v[12:13], v[2:3], 0, 64
	s_mov_b32 m0, s1
	v_readfirstlane_b32 s1, v5
	v_add_u32_e32 v5, 0x8000, v19
	global_load_lds_dwordx4 v[12:13], off
	v_lshl_add_u64 v[12:13], v[10:11], 0, 64
	s_mov_b32 m0, s1
	v_readfirstlane_b32 s1, v5
	global_load_lds_dwordx4 v[12:13], off
	s_mov_b32 m0, s1
	s_add_i32 s1, 0, 0x10000
	v_lshl_add_u64 v[12:13], v[0:1], 0, 64
	v_add_u32_e32 v5, s1, v16
	global_load_lds_dwordx4 v[12:13], off
	v_add_u32_e32 v12, v5, v164
	s_mov_b64 s[2:3], 0x80
	v_readfirstlane_b32 s1, v12
	v_lshl_add_u64 v[8:9], v[8:9], 0, s[2:3]
	s_mov_b32 m0, s1
	v_lshl_add_u64 v[2:3], v[2:3], 0, s[2:3]
	global_load_lds_dwordx4 v[8:9], off
	v_add_u32_e32 v8, v5, v165
	v_lshl_add_u64 v[0:1], v[0:1], 0, s[2:3]
	v_readfirstlane_b32 s1, v8
	v_add_u32_e32 v8, v5, v166
	s_mov_b32 m0, s1
	v_readfirstlane_b32 s1, v8
	global_load_lds_dwordx4 v[2:3], off
	v_lshl_add_u64 v[2:3], v[10:11], 0, s[2:3]
	s_mov_b32 m0, s1
	v_bfe_u32 v158, v157, 5, 1
	global_load_lds_dwordx4 v[2:3], off
	v_add_u32_e32 v2, v5, v167
	v_lshrrev_b32_e32 v14, 2, v157
	v_readfirstlane_b32 s1, v2
	s_mov_b32 m0, s1
	v_bfe_u32 v15, v157, 2, 2
	global_load_lds_dwordx4 v[0:1], off
	v_bitop3_b32 v0, v158, v14, 3 bitop3:0x78
	v_lshlrev_b32_e32 v168, 4, v0
	v_bitop3_b32 v0, v158, v15, 2 bitop3:0x36
	v_lshlrev_b32_e32 v169, 4, v0
	v_add_u32_e32 v0, 0x80, v4
	s_or_b32 s2, s24, s17
	v_ashrrev_i32_e32 v1, 31, v0
	s_ashr_i32 s3, s2, 31
	v_lshlrev_b64 v[0:1], 12, v[0:1]
	s_lshl_b64 s[2:3], s[2:3], 12
	v_lshl_add_u64 v[2:3], v[0:1], 0, s[2:3]
	s_sub_i32 s1, s19, s24
	v_or_b32_e32 v2, v2, v152
	s_and_b32 s1, s1, 0xffffff00
	v_lshl_add_u64 v[128:129], s[60:61], 0, v[2:3]
	v_lshl_add_u64 v[2:3], s[2:3], 0, v[6:7]
	s_ashr_i32 s3, s1, 31
	v_readlane_b32 s2, v247, 9
	s_add_u32 s2, s2, s1
	s_addc_u32 s3, 0, s3
	s_lshl_b64 s[2:3], s[2:3], 12
	v_lshl_add_u64 v[0:1], s[2:3], 0, v[0:1]
	v_or_b32_e32 v0, v0, v152
	v_lshl_add_u64 v[132:133], s[48:49], 0, v[0:1]
	v_lshl_add_u64 v[0:1], s[2:3], 0, v[6:7]
	v_or_b32_e32 v0, v0, v152
	v_or_b32_e32 v2, v2, v152
	v_lshl_add_u64 v[134:135], s[48:49], 0, v[0:1]
	v_mov_b32_e32 v0, 0
	v_lshl_add_u64 v[130:131], s[60:61], 0, v[2:3]
	s_mov_b64 s[2:3], 0
	s_mov_b32 s1, 0
	v_mov_b32_e32 v1, v0
	v_mov_b32_e32 v2, v0
	v_mov_b32_e32 v3, v0
	v_mov_b32_e32 v4, v0
	v_mov_b32_e32 v5, v0
	v_mov_b32_e32 v6, v0
	v_mov_b32_e32 v7, v0
	v_mov_b32_e32 v8, v0
	v_mov_b32_e32 v9, v0
	v_mov_b32_e32 v10, v0
	v_mov_b32_e32 v11, v0
	v_mov_b32_e32 v12, v0
	v_mov_b32_e32 v13, v0
	v_mov_b32_e32 v14, v0
	v_mov_b32_e32 v15, v0
	v_mov_b32_e32 v16, v0
	v_mov_b32_e32 v17, v0
	v_mov_b32_e32 v18, v0
	v_mov_b32_e32 v19, v0
	v_mov_b32_e32 v20, v0
	v_mov_b32_e32 v21, v0
	v_mov_b32_e32 v22, v0
	v_mov_b32_e32 v23, v0
	v_mov_b32_e32 v24, v0
	v_mov_b32_e32 v25, v0
	v_mov_b32_e32 v26, v0
	v_mov_b32_e32 v27, v0
	v_mov_b32_e32 v28, v0
	v_mov_b32_e32 v29, v0
	v_mov_b32_e32 v30, v0
	v_mov_b32_e32 v31, v0
; #define MFMA32(a, b, c) __builtin_amdgcn_mfma_f32_32x32x16_bf16((a), (b), (c), 0, 0, 0)
; DI void gemm_mainloop(const bf16_t* __restrict__ A, int lda, const bf16_t* __restrict__ B, int ldb, int K,
;                       f32x16 (&acc)[2][4], char* smem, const int tid) {
;     ...
;   dma_stage(A, lda, B, ldb, 0, smem, w, lane);
;   dma_stage(A, lda, B, ldb, 32, smem + STG, w, lane);
;   dma_stage(A, lda, B, ldb, 64, smem + 2 * STG, w, lane);
;   for (int kt = 0; kt < nk; ++kt) {
;     asm volatile("s_waitcnt vmcnt(8) lgkmcnt(0)" ::: "memory");
;     __builtin_amdgcn_s_barrier();
;     dma_stage(A, lda, B, ldb, (kt + 3) * 32, smem + ((kt + 3) & 3) * STG, w, lane);
;     const char* st = smem + (kt & 3) * STG;
;     _Pragma("unroll") for (int ks = 0; ks < 2; ++ks) {
;       const int oo = ks ? o1 : o0;
;       bf16x8 a0 = *(const bf16x8*)(st + aoff + oo);
;       bf16x8 a1 = *(const bf16x8*)(st + aoff + 32 * 64 + oo);
;       bf16x8 b0 = *(const bf16x8*)(st + boff + oo);
;       bf16x8 b1 = *(const bf16x8*)(st + boff + 32 * 64 + oo);
;       bf16x8 b2 = *(const bf16x8*)(st + boff + 64 * 64 + oo);
;       bf16x8 b3 = *(const bf16x8*)(st + boff + 96 * 64 + oo);
;       acc[0][0] = MFMA32(a0, b0, acc[0][0]); acc[0][1] = MFMA32(a0, b1, acc[0][1]);
;       acc[0][2] = MFMA32(a0, b2, acc[0][2]); acc[0][3] = MFMA32(a0, b3, acc[0][3]);
;       acc[1][0] = MFMA32(a1, b0, acc[1][0]); acc[1][1] = MFMA32(a1, b1, acc[1][1]);
;       acc[1][2] = MFMA32(a1, b2, acc[1][2]); acc[1][3] = MFMA32(a1, b3, acc[1][3]);
;     }
	v_mov_b32_e32 v64, v0
	v_mov_b32_e32 v65, v0
	v_mov_b32_e32 v66, v0
	v_mov_b32_e32 v67, v0
	v_mov_b32_e32 v68, v0
	v_mov_b32_e32 v69, v0
	v_mov_b32_e32 v70, v0
	v_mov_b32_e32 v71, v0
	v_mov_b32_e32 v72, v0
	v_mov_b32_e32 v73, v0
	v_mov_b32_e32 v74, v0
	v_mov_b32_e32 v75, v0
	v_mov_b32_e32 v76, v0
	v_mov_b32_e32 v77, v0
	v_mov_b32_e32 v78, v0
	v_mov_b32_e32 v79, v0
	v_mov_b32_e32 v80, v0
	v_mov_b32_e32 v81, v0
	v_mov_b32_e32 v82, v0
	v_mov_b32_e32 v83, v0
	v_mov_b32_e32 v84, v0
	v_mov_b32_e32 v85, v0
	v_mov_b32_e32 v86, v0
	v_mov_b32_e32 v87, v0
	v_mov_b32_e32 v88, v0
	v_mov_b32_e32 v89, v0
	v_mov_b32_e32 v90, v0
	v_mov_b32_e32 v91, v0
	v_mov_b32_e32 v92, v0
	v_mov_b32_e32 v93, v0
	v_mov_b32_e32 v94, v0
	v_mov_b32_e32 v95, v0
	v_mov_b32_e32 v32, v0
	v_mov_b32_e32 v33, v0
	v_mov_b32_e32 v34, v0
	v_mov_b32_e32 v35, v0
	v_mov_b32_e32 v36, v0
	v_mov_b32_e32 v37, v0
	v_mov_b32_e32 v38, v0
	v_mov_b32_e32 v39, v0
	v_mov_b32_e32 v40, v0
	v_mov_b32_e32 v41, v0
	v_mov_b32_e32 v42, v0
	v_mov_b32_e32 v43, v0
	v_mov_b32_e32 v44, v0
	v_mov_b32_e32 v45, v0
	v_mov_b32_e32 v46, v0
	v_mov_b32_e32 v47, v0
	v_mov_b32_e32 v48, v0
	v_mov_b32_e32 v49, v0
	v_mov_b32_e32 v50, v0
	v_mov_b32_e32 v51, v0
	v_mov_b32_e32 v52, v0
	v_mov_b32_e32 v53, v0
	v_mov_b32_e32 v54, v0
	v_mov_b32_e32 v55, v0
	v_mov_b32_e32 v56, v0
	v_mov_b32_e32 v57, v0
	v_mov_b32_e32 v58, v0
	v_mov_b32_e32 v59, v0
	v_mov_b32_e32 v60, v0
	v_mov_b32_e32 v61, v0
	v_mov_b32_e32 v62, v0
	v_mov_b32_e32 v63, v0
	v_mov_b32_e32 v96, v0
	v_mov_b32_e32 v97, v0
	v_mov_b32_e32 v98, v0
	v_mov_b32_e32 v99, v0
	v_mov_b32_e32 v100, v0
	v_mov_b32_e32 v101, v0
	v_mov_b32_e32 v102, v0
	v_mov_b32_e32 v103, v0
	v_mov_b32_e32 v104, v0
	v_mov_b32_e32 v105, v0
	v_mov_b32_e32 v106, v0
	v_mov_b32_e32 v107, v0
	v_mov_b32_e32 v108, v0
	v_mov_b32_e32 v109, v0
	v_mov_b32_e32 v110, v0
	v_mov_b32_e32 v111, v0
	v_mov_b32_e32 v112, v0
	v_mov_b32_e32 v113, v0
	v_mov_b32_e32 v114, v0
	v_mov_b32_e32 v115, v0
	v_mov_b32_e32 v116, v0
	v_mov_b32_e32 v117, v0
	v_mov_b32_e32 v118, v0
	v_mov_b32_e32 v119, v0
	v_mov_b32_e32 v120, v0
	v_mov_b32_e32 v121, v0
	v_mov_b32_e32 v122, v0
	v_mov_b32_e32 v123, v0
	v_mov_b32_e32 v124, v0
	v_mov_b32_e32 v125, v0
	v_mov_b32_e32 v126, v0
	v_mov_b32_e32 v127, v0
	s_mov_b64 s[24:25], 0xc0
	s_mov_b64 s[26:27], 0x100
	v_add_u32_e32 v205, v163, v164
	v_add_u32_e32 v195, v161, v168
	v_add_u32_e32 v196, v162, v168
	v_readfirstlane_b32 s17, v205
	v_add_u32_e32 v152, v161, v169
	v_add_u32_e32 v194, v162, v169
	s_waitcnt vmcnt(8) lgkmcnt(0)
	s_barrier
	ds_read_b128 v[170:173], v195
	ds_read_b128 v[174:177], v195 offset:2048
	ds_read_b128 v[178:181], v196 offset:16384
	ds_read_b128 v[182:185], v196 offset:18432
	ds_read_b128 v[186:189], v196 offset:20480
	ds_read_b128 v[190:193], v196 offset:22528
	ds_read_b128 v[212:215], v152
	ds_read_b128 v[216:219], v152 offset:2048
	ds_read_b128 v[220:223], v194 offset:16384
	ds_read_b128 v[224:227], v194 offset:18432
	ds_read_b128 v[228:231], v194 offset:20480
	ds_read_b128 v[232:235], v194 offset:22528
	s_add_u32 m0, s17, 0x18000
	v_lshl_add_u64 v[136:137], v[130:131], 0, s[24:25]
	v_lshl_add_u64 v[138:139], v[128:129], 0, s[24:25]
	global_load_lds_dwordx4 v[136:137], off
	s_add_u32 m0, s17, 0x1a000
	v_lshl_add_u64 v[136:137], v[134:135], 0, s[24:25]
	global_load_lds_dwordx4 v[138:139], off
	s_add_u32 m0, s17, 0x1c000
	v_lshl_add_u64 v[138:139], v[132:133], 0, s[24:25]
	global_load_lds_dwordx4 v[136:137], off
	s_add_u32 m0, s17, 0x1e000
	s_add_u32 s24, s24, 64
	global_load_lds_dwordx4 v[138:139], off
	s_addc_u32 s25, s25, 0
.Lgm_p5o_loop:
	s_waitcnt lgkmcnt(6)
	v_mfma_f32_32x32x16_bf16 v[112:127], v[170:173], v[178:181], v[112:127]
	v_mfma_f32_32x32x16_bf16 v[96:111], v[170:173], v[182:185], v[96:111]
	v_mfma_f32_32x32x16_bf16 v[48:63], v[170:173], v[186:189], v[48:63]
	v_mfma_f32_32x32x16_bf16 v[32:47], v[170:173], v[190:193], v[32:47]
	v_mfma_f32_32x32x16_bf16 v[80:95], v[174:177], v[178:181], v[80:95]
	v_mfma_f32_32x32x16_bf16 v[64:79], v[174:177], v[182:185], v[64:79]
	v_mfma_f32_32x32x16_bf16 v[16:31], v[174:177], v[186:189], v[16:31]
	v_mfma_f32_32x32x16_bf16 v[0:15], v[174:177], v[190:193], v[0:15]
	s_waitcnt vmcnt(8) lgkmcnt(0)
	s_barrier
	ds_read_b128 v[170:173], v195 offset:32768
	ds_read_b128 v[174:177], v195 offset:34816
	ds_read_b128 v[178:181], v196 offset:49152
	ds_read_b128 v[182:185], v196 offset:51200
	ds_read_b128 v[186:189], v196 offset:53248
	ds_read_b128 v[190:193], v196 offset:55296
	v_mfma_f32_32x32x16_bf16 v[112:127], v[212:215], v[220:223], v[112:127]
	s_mov_b32 m0, s17
	v_lshl_add_u64 v[136:137], v[130:131], 0, s[24:25]
	v_mfma_f32_32x32x16_bf16 v[96:111], v[212:215], v[224:227], v[96:111]
	global_load_lds_dwordx4 v[136:137], off
	s_add_u32 m0, s17, 0x2000
	v_lshl_add_u64 v[138:139], v[128:129], 0, s[24:25]
	v_mfma_f32_32x32x16_bf16 v[48:63], v[212:215], v[228:231], v[48:63]
	global_load_lds_dwordx4 v[138:139], off
	s_add_u32 m0, s17, 0x4000
	v_lshl_add_u64 v[136:137], v[134:135], 0, s[24:25]
	v_mfma_f32_32x32x16_bf16 v[32:47], v[212:215], v[232:235], v[32:47]
	global_load_lds_dwordx4 v[136:137], off
	s_add_u32 m0, s17, 0x6000
	v_lshl_add_u64 v[138:139], v[132:133], 0, s[24:25]
	v_mfma_f32_32x32x16_bf16 v[80:95], v[216:219], v[220:223], v[80:95]
	global_load_lds_dwordx4 v[138:139], off
	s_add_u32 s24, s24, 64
	s_addc_u32 s25, s25, 0
	v_mfma_f32_32x32x16_bf16 v[64:79], v[216:219], v[224:227], v[64:79]
	v_mfma_f32_32x32x16_bf16 v[16:31], v[216:219], v[228:231], v[16:31]
	v_mfma_f32_32x32x16_bf16 v[0:15], v[216:219], v[232:235], v[0:15]
	ds_read_b128 v[212:215], v152 offset:32768
	ds_read_b128 v[216:219], v152 offset:34816
	ds_read_b128 v[220:223], v194 offset:49152
	ds_read_b128 v[224:227], v194 offset:51200
	ds_read_b128 v[228:231], v194 offset:53248
	ds_read_b128 v[232:235], v194 offset:55296
	v_xor_b32_e32 v195, 0x10000, v195
	v_xor_b32_e32 v196, 0x10000, v196
	v_xor_b32_e32 v152, 0x10000, v152
	v_xor_b32_e32 v194, 0x10000, v194
	s_waitcnt lgkmcnt(6)
	v_mfma_f32_32x32x16_bf16 v[112:127], v[170:173], v[178:181], v[112:127]
	v_mfma_f32_32x32x16_bf16 v[96:111], v[170:173], v[182:185], v[96:111]
	v_mfma_f32_32x32x16_bf16 v[48:63], v[170:173], v[186:189], v[48:63]
	v_mfma_f32_32x32x16_bf16 v[32:47], v[170:173], v[190:193], v[32:47]
	v_mfma_f32_32x32x16_bf16 v[80:95], v[174:177], v[178:181], v[80:95]
	v_mfma_f32_32x32x16_bf16 v[64:79], v[174:177], v[182:185], v[64:79]
	v_mfma_f32_32x32x16_bf16 v[16:31], v[174:177], v[186:189], v[16:31]
	v_mfma_f32_32x32x16_bf16 v[0:15], v[174:177], v[190:193], v[0:15]
	s_waitcnt vmcnt(8) lgkmcnt(0)
	s_barrier
; DI void gemm_mainloop(const bf16_t* __restrict__ A, int lda, const bf16_t* __restrict__ B, int ldb, int K,
;                       f32x16 (&acc)[2][4], char* smem, const int tid) {
;     ...
;   for (int kt = 0; kt < nk; ++kt) {
;     asm volatile("s_waitcnt vmcnt(8) lgkmcnt(0)" ::: "memory");
;     __builtin_amdgcn_s_barrier();
;     dma_stage(A, lda, B, ldb, (kt + 3) * 32, smem + ((kt + 3) & 3) * STG, w, lane);
;     const char* st = smem + (kt & 3) * STG;
;     _Pragma("unroll") for (int ks = 0; ks < 2; ++ks) {
;       const int oo = ks ? o1 : o0;
;       bf16x8 a0 = *(const bf16x8*)(st + aoff + oo);
;       bf16x8 a1 = *(const bf16x8*)(st + aoff + 32 * 64 + oo);
;       bf16x8 b0 = *(const bf16x8*)(st + boff + oo);
;       bf16x8 b1 = *(const bf16x8*)(st + boff + 32 * 64 + oo);
;       bf16x8 b2 = *(const bf16x8*)(st + boff + 64 * 64 + oo);
;       bf16x8 b3 = *(const bf16x8*)(st + boff + 96 * 64 + oo);
;       acc[0][0] = MFMA32(a0, b0, acc[0][0]); acc[0][1] = MFMA32(a0, b1, acc[0][1]);
;       acc[0][2] = MFMA32(a0, b2, acc[0][2]); acc[0][3] = MFMA32(a0, b3, acc[0][3]);
;       acc[1][0] = MFMA32(a1, b0, acc[1][0]); acc[1][1] = MFMA32(a1, b1, acc[1][1]);
;       acc[1][2] = MFMA32(a1, b2, acc[1][2]); acc[1][3] = MFMA32(a1, b3, acc[1][3]);
;     }
;   }
;   asm volatile("s_waitcnt vmcnt(0)" ::: "memory");
;   __syncthreads();
; DI void p5_tile(const Params& P, int l, int half, int t, char* smem) {
;     ...
;   _Pragma("unroll") for (int seg = 0; seg < 2; ++seg) {
;     const int gc = n0 + wn * 128 + seg * 64 + ch * 8;
;     _Pragma("unroll") for (int mi = 0; mi < 2; ++mi) {
;       stage_block(acc[mi][2 * seg], acc[mi][2 * seg + 1], sE, r, h);
;       _Pragma("unroll") for (int ps = 0; ps < 4; ++ps) {
;         const int rr = ps * 8 + (lane >> 3);
;         const int m = m0 + wm * 64 + mi * 32 + rr;
;         const size_t off = (size_t)m * DM + gc;
;         float v[8]; read8(sE + rr * EST + ch * 8, v);
;         float x[8]; read8(xin + off, x);
;         _Pragma("unroll") for (int j = 0; j < 8; ++j) v[j] += x[j];
;         *(float4*)(xo + off) = make_float4(v[0], v[1], v[2], v[3]);
;         *(float4*)(xo + off + 4) = make_float4(v[4], v[5], v[6], v[7]);
;         if (l < DEPTH - 1) {
;           *(u32x4*)(xbo + off) = pack8u(v);
;           float sq = red8(sum8sq(v));
;           if (ch == 0) sqn[(size_t)m * 32 + ((n0 + wn * 128 + seg * 64) >> 6)] = sq;
;         }
	ds_read_b128 v[170:173], v195
	ds_read_b128 v[174:177], v195 offset:2048
	ds_read_b128 v[178:181], v196 offset:16384
	ds_read_b128 v[182:185], v196 offset:18432
	ds_read_b128 v[186:189], v196 offset:20480
	ds_read_b128 v[190:193], v196 offset:22528
	v_mfma_f32_32x32x16_bf16 v[112:127], v[212:215], v[220:223], v[112:127]
	s_add_u32 m0, s17, 0x8000
	v_lshl_add_u64 v[136:137], v[130:131], 0, s[24:25]
	v_mfma_f32_32x32x16_bf16 v[96:111], v[212:215], v[224:227], v[96:111]
	global_load_lds_dwordx4 v[136:137], off
	s_add_u32 m0, s17, 0xa000
	v_lshl_add_u64 v[138:139], v[128:129], 0, s[24:25]
	v_mfma_f32_32x32x16_bf16 v[48:63], v[212:215], v[228:231], v[48:63]
	global_load_lds_dwordx4 v[138:139], off
	s_add_u32 m0, s17, 0xc000
	v_lshl_add_u64 v[136:137], v[134:135], 0, s[24:25]
	v_mfma_f32_32x32x16_bf16 v[32:47], v[212:215], v[232:235], v[32:47]
	global_load_lds_dwordx4 v[136:137], off
	s_add_u32 m0, s17, 0xe000
	v_lshl_add_u64 v[138:139], v[132:133], 0, s[24:25]
	v_mfma_f32_32x32x16_bf16 v[80:95], v[216:219], v[220:223], v[80:95]
	global_load_lds_dwordx4 v[138:139], off
	s_add_u32 s24, s24, 64
	s_addc_u32 s25, s25, 0
	v_mfma_f32_32x32x16_bf16 v[64:79], v[216:219], v[224:227], v[64:79]
	v_mfma_f32_32x32x16_bf16 v[16:31], v[216:219], v[228:231], v[16:31]
	v_mfma_f32_32x32x16_bf16 v[0:15], v[216:219], v[232:235], v[0:15]
	ds_read_b128 v[212:215], v152
	ds_read_b128 v[216:219], v152 offset:2048
	ds_read_b128 v[220:223], v194 offset:16384
	ds_read_b128 v[224:227], v194 offset:18432
	ds_read_b128 v[228:231], v194 offset:20480
	ds_read_b128 v[232:235], v194 offset:22528
	s_xor_b32 s17, s17, 0x10000
	s_add_u32 s2, s2, 0x80
	s_cmpk_lg_i32 s2, 0x1000
	s_cbranch_scc1 .Lgm_p5o_loop
	s_waitcnt lgkmcnt(0)
	s_mov_b64 s[24:25], 0xc0
	s_movk_i32 s1, 0x2200
	v_mul_lo_u32 v128, v159, s1
	v_mul_u32_u24_e32 v129, 0x110, v158
	v_add_u32_e32 v130, 0, v128
	v_lshlrev_b32_e32 v129, 2, v129
	v_lshlrev_b32_e32 v132, 2, v156
	v_add3_u32 v134, v130, v129, v132
	v_add3_u32 v135, v130, v132, v129
	v_and_b32_e32 v131, 7, v157
	v_lshrrev_b32_e32 v129, 3, v154
	v_add_u32_e32 v143, s0, v155
	v_add_u32_e32 v136, 0x800, v134
	v_add_u32_e32 v137, 0x800, v135
	v_add_u32_e32 v140, 0x1000, v135
	s_waitcnt vmcnt(0)
	s_waitcnt vmcnt(0)
	s_barrier
	v_or_b32_e32 v128, s16, v160
	v_lshlrev_b32_e32 v152, 3, v131
	ds_write2_b32 v134, v112, v113 offset1:68
	ds_write2_b32 v135, v96, v97 offset0:32 offset1:100
	ds_write2_b32 v134, v114, v115 offset0:136 offset1:204
	ds_write2_b32 v135, v98, v99 offset0:168 offset1:236
	ds_write2_b32 v136, v116, v117 offset0:32 offset1:100
	ds_write2_b32 v137, v100, v101 offset0:64 offset1:132
	ds_write2_b32 v136, v118, v119 offset0:168 offset1:236
	ds_write2_b32 v140, v104, v105 offset0:96 offset1:164
	v_or_b32_e32 v104, v143, v129
	v_or_b32_e32 v132, v128, v152
	v_add_u32_e32 v141, 0x1200, v134
	v_ashrrev_i32_e32 v105, 31, v104
	v_ashrrev_i32_e32 v133, 31, v132
	ds_write2_b32 v141, v122, v123 offset0:72 offset1:140
	v_add_u32_e32 v123, 0x1200, v135
	v_add_u32_e32 v142, 0x1800, v134
	v_lshlrev_b64 v[112:113], 11, v[104:105]
	ds_write2_b32 v123, v106, v107 offset0:104 offset1:172
	ds_write2_b32 v142, v124, v125 offset0:96 offset1:164
	v_add_u32_e32 v125, 0x1a00, v134
	v_lshl_add_u64 v[106:107], v[112:113], 0, v[132:133]
	v_lshl_add_u32 v154, v131, 5, v130
	v_add_u32_e32 v138, 0xa00, v135
	v_add_u32_e32 v139, 0x1000, v134
	v_add_u32_e32 v124, 0x1800, v135
	ds_write2_b32 v125, v126, v127 offset0:104 offset1:172
	v_add_u32_e32 v126, 0x1c00, v135
	s_movk_i32 s2, 0x110
	v_lshlrev_b64 v[118:119], 2, v[106:107]
	ds_write2_b32 v138, v102, v103 offset0:72 offset1:140
	ds_write2_b32 v139, v120, v121 offset0:64 offset1:132
	ds_write2_b32 v124, v108, v109 offset0:128 offset1:196
	ds_write2_b32 v126, v110, v111 offset0:8 offset1:76
	v_mad_u32_u24 v102, v129, s2, v154
	v_lshl_add_u64 v[100:101], s[8:9], 0, v[118:119]
	ds_read_b128 v[96:99], v102
	ds_read_b128 v[108:111], v102 offset:16
	global_load_dwordx4 v[114:117], v[100:101], off offset:16
	s_nop 0
	global_load_dwordx4 v[100:103], v[100:101], off
	v_ashrrev_i32_e32 v130, 6, v128
	v_cmp_eq_u32_e64 s[0:1], 0, v131
	v_ashrrev_i32_e32 v131, 31, v130
	v_lshl_add_u64 v[130:131], v[130:131], 2, s[12:13]
	s_andn2_b64 vcc, exec, s[14:15]
	s_waitcnt vmcnt(0) lgkmcnt(1)
	v_pk_add_f32 v[100:101], v[96:97], v[100:101]
	v_pk_add_f32 v[102:103], v[98:99], v[102:103]
	s_waitcnt lgkmcnt(0)
	v_pk_add_f32 v[96:97], v[108:109], v[114:115]
	v_lshl_add_u64 v[108:109], s[6:7], 0, v[118:119]
	v_pk_add_f32 v[98:99], v[110:111], v[116:117]
	global_store_dwordx4 v[108:109], v[100:103], off
	global_store_dwordx4 v[108:109], v[96:99], off offset:16
	v_cndmask_b32_e64 v108, 0, 1, s[14:15]
	v_cmp_ne_u32_e64 s[2:3], 1, v108
	s_cbranch_vccnz .LBB0_666
	v_cvt_pk_bf16_f32 v108, v100, v101
	v_pk_mul_f32 v[100:101], v[100:101], v[100:101]
	v_cvt_pk_bf16_f32 v109, v102, v103
	v_pk_mul_f32 v[102:103], v[102:103], v[102:103]
	v_add_f32_e32 v100, v100, v101
	v_add_f32_e32 v100, v102, v100
	v_cvt_pk_bf16_f32 v110, v96, v97
	v_pk_mul_f32 v[96:97], v[96:97], v[96:97]
	v_add_f32_e32 v100, v103, v100
	v_add_f32_e32 v96, v96, v100
	v_add_f32_e32 v96, v97, v96
	v_xor_b32_e32 v97, 1, v145
	v_cvt_pk_bf16_f32 v111, v98, v99
	v_pk_mul_f32 v[98:99], v[98:99], v[98:99]
	v_cmp_lt_i32_e32 vcc, v97, v198
	v_add_f32_e32 v96, v98, v96
	v_add_f32_e32 v96, v99, v96
	v_cndmask_b32_e32 v97, v145, v97, vcc
	v_lshlrev_b32_e32 v97, 2, v97
	ds_bpermute_b32 v97, v97, v96
	v_lshl_add_u64 v[106:107], v[106:107], 1, s[10:11]
	global_store_dwordx4 v[106:107], v[108:111], off
	s_waitcnt lgkmcnt(0)
	v_add_f32_e32 v96, v96, v97
	v_xor_b32_e32 v97, 2, v145
	v_cmp_lt_i32_e32 vcc, v97, v198
	s_nop 1
	v_cndmask_b32_e32 v97, v145, v97, vcc
	v_lshlrev_b32_e32 v97, 2, v97
	ds_bpermute_b32 v97, v97, v96
	s_waitcnt lgkmcnt(0)
	v_add_f32_e32 v96, v96, v97
	v_xor_b32_e32 v97, 4, v145
	v_cmp_lt_i32_e32 vcc, v97, v198
	s_nop 1
	v_cndmask_b32_e32 v97, v145, v97, vcc
	v_lshlrev_b32_e32 v97, 2, v97
	ds_bpermute_b32 v97, v97, v96
	s_and_saveexec_b64 s[16:17], s[0:1]
	s_cbranch_execz .LBB0_665
	s_waitcnt lgkmcnt(0)
	v_add_f32_e32 v98, v96, v97
	v_lshlrev_b64 v[96:97], 7, v[104:105]
	v_lshl_add_u64 v[96:97], v[130:131], 0, v[96:97]
	global_store_dword v[96:97], v98, off

; #define MFMA32(a, b, c) __builtin_amdgcn_mfma_f32_32x32x16_bf16((a), (b), (c), 0, 0, 0)
; DI f32x16 zero16() { f32x16 z; _Pragma("unroll") for (int i = 0; i < 16; ++i) z[i] = 0.f; return z; }
; DI void attn_item(const Params& P, int half, int item, char* smem) {
;     ...
;     asm volatile("s_waitcnt vmcnt(5) lgkmcnt(0)" ::: "memory");
;     __builtin_amdgcn_s_barrier();
;     {
;       const int nxt = (cur == 0) ? 2 : cur - 1;
;       attn_dma_k(P, head, tkb + (kt + 2) * 64, smem, nxt, w, lane);
;       attn_dma_v(P, head, tkb + (kt + 2) * 64, smem, nxt, w, lane);
;     }
;     const char* kn = smem + cur * 40960;
;     const char* kr = kn + 16384;
;     f32x16 st[2]; st[0] = zero16(); st[1] = zero16();
;     _Pragma("unroll") for (int s = 0; s < 8; ++s) {
;       const int po = ((2 * s + h) ^ rn) << 4;
;       bf16x8 a0 = *(const bf16x8*)(kn + r * 256 + po);
;       bf16x8 a1 = *(const bf16x8*)(kn + (32 + r) * 256 + po);
;       st[0] = MFMA32(a0, qf[s], st[0]);
;       st[1] = MFMA32(a1, qf[s], st[1]);
;     }
;     _Pragma("unroll") for (int s = 0; s < 4; ++s) {
;       const int po = ((2 * s + h) ^ rr8) << 4;
;       bf16x8 a0 = *(const bf16x8*)(kr + r * 128 + po);
;       bf16x8 a1 = *(const bf16x8*)(kr + (32 + r) * 128 + po);
;       st[0] = MFMA32(a0, qf[8 + s], st[0]);
;       st[1] = MFMA32(a1, qf[8 + s], st[1]);
;     }
.LBB0_729:
	s_mul_i32 s16, s13, 0xa000
	s_add_i32 s1, s16, 0xffff6000
	s_cmp_lg_u32 s13, 0
	s_cselect_b32 s1, s1, 0x14000
	v_mov_b32_e32 v197, v64
	s_add_u32 s80, s1, s82
	s_add_u32 s81, s80, 0x2000
	s_add_u32 s83, s80, 0x4000
	s_add_u32 s90, s80, 0x6000
	s_add_u32 s91, s80, 0x8000
	s_lshl_b32 s84, s0, 11
	s_mov_b32 s85, 0
	s_lshl_b32 s86, s0, 7
	s_mov_b32 s87, 0
	s_ashr_i32 s1, s0, 31
	s_lshl_b64 s[14:15], s[0:1], 1
	s_mov_b32 s1, s16
	v_add_u32_e32 v152, s1, v173
	s_waitcnt vmcnt(5) lgkmcnt(0)
	s_barrier
	v_add_u32_e32 v68, v152, v175
	ds_read_b128 v[64:67], v68
	ds_read_b128 v[68:71], v68 offset:8192
	v_add_u32_e32 v195, v152, v176
	ds_read_b128 v[206:209], v195
	ds_read_b128 v[210:213], v195 offset:8192
	v_add_u32_e32 v195, v152, v177
	ds_read_b128 v[214:217], v195
	ds_read_b128 v[252:255], v195 offset:8192
	v_add_u32_e32 v205, s1, v174
	v_cmp_lt_i32_e32 vcc, v199, v198
	s_add_i32 s1, s13, 1
	s_cmp_lg_u32 s13, 2
	s_cselect_b32 s13, s1, 0
	s_add_i32 s12, s12, -1
	s_add_i32 s0, s0, 64
	s_cmp_lg_u32 s12, 0
	s_waitcnt lgkmcnt(4)
	v_mfma_f32_32x32x16_bf16 v[80:95], v[64:67], v[96:99], 0
	v_mfma_f32_32x32x16_bf16 v[64:79], v[68:71], v[96:99], 0
	s_waitcnt lgkmcnt(2)
	v_mfma_f32_32x32x16_bf16 v[80:95], v[206:209], v[100:103], v[80:95]
	v_mfma_f32_32x32x16_bf16 v[64:79], v[210:213], v[100:103], v[64:79]
	v_add_u32_e32 v195, v152, v178
	ds_read_b128 v[206:209], v195
	ds_read_b128 v[210:213], v195 offset:8192
	s_mov_b32 m0, s80
	v_lshl_add_u64 v[168:169], v[156:157], 0, s[84:85]
	global_load_lds_dwordx4 v[168:169], off
	s_waitcnt lgkmcnt(2)
	v_mfma_f32_32x32x16_bf16 v[80:95], v[214:217], v[104:107], v[80:95]
	v_mfma_f32_32x32x16_bf16 v[64:79], v[252:255], v[104:107], v[64:79]
	v_add_u32_e32 v195, v152, v179
	ds_read_b128 v[214:217], v195
	ds_read_b128 v[252:255], v195 offset:8192
	s_waitcnt lgkmcnt(2)
	v_mfma_f32_32x32x16_bf16 v[80:95], v[206:209], v[108:111], v[80:95]
	v_mfma_f32_32x32x16_bf16 v[64:79], v[210:213], v[108:111], v[64:79]
	v_add_u32_e32 v195, v152, v180
	ds_read_b128 v[206:209], v195
	ds_read_b128 v[210:213], v195 offset:8192
	s_mov_b32 m0, s81
	v_lshl_add_u64 v[170:171], v[158:159], 0, s[84:85]
	global_load_lds_dwordx4 v[170:171], off
	s_waitcnt lgkmcnt(2)
	v_mfma_f32_32x32x16_bf16 v[80:95], v[214:217], v[112:115], v[80:95]
	v_mfma_f32_32x32x16_bf16 v[64:79], v[252:255], v[112:115], v[64:79]
	v_add_u32_e32 v195, v152, v181
	ds_read_b128 v[214:217], v195
	ds_read_b128 v[252:255], v195 offset:8192
	s_waitcnt lgkmcnt(2)
	v_mfma_f32_32x32x16_bf16 v[80:95], v[206:209], v[116:119], v[80:95]
	v_mfma_f32_32x32x16_bf16 v[64:79], v[210:213], v[116:119], v[64:79]
	v_add_u32_e32 v195, v152, v182
	ds_read_b128 v[206:209], v195
	ds_read_b128 v[210:213], v195 offset:8192
	s_mov_b32 m0, s83
	v_lshl_add_u64 v[168:169], v[160:161], 0, s[86:87]
	global_load_lds_dwordx4 v[168:169], off
	s_waitcnt lgkmcnt(2)
	v_mfma_f32_32x32x16_bf16 v[80:95], v[214:217], v[120:123], v[80:95]
	v_mfma_f32_32x32x16_bf16 v[64:79], v[252:255], v[120:123], v[64:79]
	v_add_u32_e32 v195, v205, v183
	ds_read_b128 v[214:217], v195 offset:16384
	ds_read_b128 v[252:255], v195 offset:20480
	s_waitcnt lgkmcnt(2)
	v_mfma_f32_32x32x16_bf16 v[80:95], v[206:209], v[124:127], v[80:95]
	v_mfma_f32_32x32x16_bf16 v[64:79], v[210:213], v[124:127], v[64:79]
	v_add_u32_e32 v195, v205, v184
	ds_read_b128 v[206:209], v195 offset:16384
	ds_read_b128 v[210:213], v195 offset:20480
	s_mov_b32 m0, s90
	v_lshl_add_u64 v[170:171], v[162:163], 0, s[14:15]
	global_load_lds_dwordx4 v[170:171], off
	s_waitcnt lgkmcnt(2)
	v_mfma_f32_32x32x16_bf16 v[80:95], v[214:217], v[128:131], v[80:95]
	v_mfma_f32_32x32x16_bf16 v[64:79], v[252:255], v[128:131], v[64:79]
	v_add_u32_e32 v195, v205, v185
	ds_read_b128 v[214:217], v195 offset:16384
	ds_read_b128 v[252:255], v195 offset:20480
	s_waitcnt lgkmcnt(2)
	v_mfma_f32_32x32x16_bf16 v[80:95], v[206:209], v[132:135], v[80:95]
	v_mfma_f32_32x32x16_bf16 v[64:79], v[210:213], v[132:135], v[64:79]
	v_add_u32_e32 v195, v205, v186
	ds_read_b128 v[206:209], v195 offset:16384
	ds_read_b128 v[210:213], v195 offset:20480
	s_mov_b32 m0, s91
	v_lshl_add_u64 v[168:169], v[164:165], 0, s[14:15]
	global_load_lds_dwordx4 v[168:169], off
	v_add_u32_e32 v205, v205, v167
	s_waitcnt lgkmcnt(2)
	v_mfma_f32_32x32x16_bf16 v[80:95], v[214:217], v[136:139], v[80:95]
	v_mfma_f32_32x32x16_bf16 v[64:79], v[252:255], v[136:139], v[64:79]
	s_waitcnt lgkmcnt(0)
; DI void attn_item(const Params& P, int half, int item, char* smem) {
;     ...
;     float mx = st[0][0];
;     _Pragma("unroll") for (int i = 0; i < 16; ++i) { mx = fmaxf(mx, st[0][i]); mx = fmaxf(mx, st[1][i]); }
;     mx = fmaxf(mx, __shfl_xor(mx, 32));
;     const float mnew = fmaxf(mrun, mx);
;     const float alpha = __builtin_amdgcn_exp2f(mrun - mnew);
;     mrun = mnew;
;     float psum = 0.f;
;     _Pragma("unroll") for (int i = 0; i < 16; ++i) {
;       st[0][i] = __builtin_amdgcn_exp2f(st[0][i] - mnew); psum += st[0][i];
;       st[1][i] = __builtin_amdgcn_exp2f(st[1][i] - mnew); psum += st[1][i];
;     }
;     lrun = lrun * alpha + psum;
;     _Pragma("unroll") for (int mt = 0; mt < 4; ++mt) {
;       _Pragma("unroll") for (int i = 0; i < 16; ++i) o[mt][i] *= alpha;
;     }
	v_mfma_f32_32x32x16_bf16 v[80:95], v[206:209], v[140:143], v[80:95]
	v_mfma_f32_32x32x16_bf16 v[64:79], v[210:213], v[140:143], v[64:79]
	s_nop 10
	v_max_f32_e32 v195, v80, v80
	v_max_f32_e32 v152, v64, v64
	v_max_f32_e32 v152, v195, v152
	v_max3_f32 v152, v152, v81, v65
	v_max3_f32 v152, v152, v82, v66
	v_max3_f32 v152, v152, v83, v67
	v_max3_f32 v152, v152, v84, v68
	v_max3_f32 v152, v152, v85, v69
	v_max3_f32 v152, v152, v86, v70
	v_max3_f32 v152, v152, v87, v71
	v_max3_f32 v152, v152, v88, v72
	v_max3_f32 v152, v152, v89, v73
	v_max3_f32 v152, v152, v90, v74
	v_max3_f32 v152, v152, v91, v75
	v_max3_f32 v152, v152, v92, v76
	v_max3_f32 v152, v152, v93, v77
	v_max3_f32 v152, v152, v94, v78
	v_max3_f32 v195, v152, v95, v79
	v_cndmask_b32_e32 v152, v145, v199, vcc
	v_lshlrev_b32_e32 v152, 2, v152
	ds_bpermute_b32 v206, v152, v195
	s_waitcnt lgkmcnt(0)
	v_max3_f32 v195, v196, v195, v206
	v_sub_f32_e32 v64, v64, v195
	v_exp_f32_e32 v206, v64
	v_sub_f32_e32 v64, v81, v195
	v_exp_f32_e32 v81, v64
	v_sub_f32_e32 v64, v65, v195
	v_exp_f32_e32 v65, v64
	v_sub_f32_e32 v64, v82, v195
	v_exp_f32_e32 v82, v64
	v_sub_f32_e32 v64, v66, v195
	v_exp_f32_e32 v207, v64
	v_sub_f32_e32 v64, v83, v195
	v_exp_f32_e32 v83, v64
	v_sub_f32_e32 v64, v67, v195
	v_exp_f32_e32 v208, v64
	v_sub_f32_e32 v64, v84, v195
	v_exp_f32_e32 v84, v64
	v_sub_f32_e32 v64, v68, v195
	v_exp_f32_e32 v209, v64
	v_sub_f32_e32 v64, v85, v195
	v_exp_f32_e32 v68, v64
	v_sub_f32_e32 v64, v69, v195
	v_exp_f32_e32 v85, v64
	v_sub_f32_e32 v64, v86, v195
	v_exp_f32_e32 v69, v64
	v_sub_f32_e32 v64, v70, v195
	v_exp_f32_e32 v86, v64
	v_sub_f32_e32 v64, v87, v195
	v_exp_f32_e32 v70, v64
	v_sub_f32_e32 v64, v71, v195
	v_exp_f32_e32 v87, v64
	v_sub_f32_e32 v64, v88, v195
	v_exp_f32_e32 v88, v64
	v_sub_f32_e32 v64, v72, v195
	v_exp_f32_e32 v210, v64
	v_sub_f32_e32 v64, v89, v195
	v_exp_f32_e32 v89, v64
	v_sub_f32_e32 v64, v73, v195
	v_exp_f32_e32 v211, v64
	v_sub_f32_e32 v64, v90, v195
	v_exp_f32_e32 v90, v64
	v_sub_f32_e32 v64, v74, v195
	v_exp_f32_e32 v212, v64
	v_sub_f32_e32 v64, v91, v195
	v_exp_f32_e32 v91, v64
	v_sub_f32_e32 v64, v75, v195
	v_exp_f32_e32 v213, v64
	v_sub_f32_e32 v64, v92, v195
	v_exp_f32_e32 v92, v64
	v_sub_f32_e32 v64, v76, v195
	v_exp_f32_e32 v214, v64
	v_sub_f32_e32 v64, v93, v195
	v_sub_f32_e32 v80, v80, v195
	v_exp_f32_e32 v93, v64
	v_sub_f32_e32 v64, v77, v195
	v_exp_f32_e32 v80, v80
	v_exp_f32_e32 v215, v64
	v_sub_f32_e32 v64, v94, v195
	v_exp_f32_e32 v94, v64
	v_sub_f32_e32 v64, v78, v195
	v_exp_f32_e32 v216, v64
	v_sub_f32_e32 v64, v95, v195
	v_exp_f32_e32 v95, v64
	v_sub_f32_e32 v64, v79, v195
	v_exp_f32_e32 v217, v64
	v_sub_f32_e32 v196, v196, v195
	v_exp_f32_e32 v196, v196
	v_add_f32_e32 v64, 0, v80
	v_add_f32_e32 v64, v206, v64
	v_add_f32_e32 v64, v81, v64
	v_cmp_neq_f32_e32 vcc, 1.0, v196
	s_cbranch_vccz .Lattn_norescale
	v_pk_mul_f32 v[0:1], v[0:1], v[196:197] op_sel_hi:[1,0]
	v_pk_mul_f32 v[2:3], v[2:3], v[196:197] op_sel_hi:[1,0]
	v_pk_mul_f32 v[4:5], v[4:5], v[196:197] op_sel_hi:[1,0]
	v_pk_mul_f32 v[6:7], v[6:7], v[196:197] op_sel_hi:[1,0]
	v_pk_mul_f32 v[8:9], v[8:9], v[196:197] op_sel_hi:[1,0]
	v_pk_mul_f32 v[10:11], v[10:11], v[196:197] op_sel_hi:[1,0]
	v_pk_mul_f32 v[12:13], v[12:13], v[196:197] op_sel_hi:[1,0]
	v_pk_mul_f32 v[14:15], v[14:15], v[196:197] op_sel_hi:[1,0]
	v_pk_mul_f32 v[16:17], v[16:17], v[196:197] op_sel_hi:[1,0]
	v_pk_mul_f32 v[18:19], v[18:19], v[196:197] op_sel_hi:[1,0]
	v_pk_mul_f32 v[20:21], v[20:21], v[196:197] op_sel_hi:[1,0]
	v_pk_mul_f32 v[22:23], v[22:23], v[196:197] op_sel_hi:[1,0]
	v_pk_mul_f32 v[24:25], v[24:25], v[196:197] op_sel_hi:[1,0]
	v_pk_mul_f32 v[26:27], v[26:27], v[196:197] op_sel_hi:[1,0]
	v_pk_mul_f32 v[28:29], v[28:29], v[196:197] op_sel_hi:[1,0]
	v_pk_mul_f32 v[30:31], v[30:31], v[196:197] op_sel_hi:[1,0]
	v_pk_mul_f32 v[32:33], v[32:33], v[196:197] op_sel_hi:[1,0]
	v_pk_mul_f32 v[34:35], v[34:35], v[196:197] op_sel_hi:[1,0]
	v_pk_mul_f32 v[36:37], v[36:37], v[196:197] op_sel_hi:[1,0]
	v_pk_mul_f32 v[38:39], v[38:39], v[196:197] op_sel_hi:[1,0]
	v_pk_mul_f32 v[40:41], v[40:41], v[196:197] op_sel_hi:[1,0]
	v_pk_mul_f32 v[42:43], v[42:43], v[196:197] op_sel_hi:[1,0]
	v_pk_mul_f32 v[44:45], v[44:45], v[196:197] op_sel_hi:[1,0]
	v_pk_mul_f32 v[46:47], v[46:47], v[196:197] op_sel_hi:[1,0]
	v_pk_mul_f32 v[48:49], v[48:49], v[196:197] op_sel_hi:[1,0]
	v_pk_mul_f32 v[50:51], v[50:51], v[196:197] op_sel_hi:[1,0]
	v_pk_mul_f32 v[52:53], v[52:53], v[196:197] op_sel_hi:[1,0]
	v_pk_mul_f32 v[54:55], v[54:55], v[196:197] op_sel_hi:[1,0]
	v_pk_mul_f32 v[56:57], v[56:57], v[196:197] op_sel_hi:[1,0]
	v_pk_mul_f32 v[58:59], v[58:59], v[196:197] op_sel_hi:[1,0]
	v_pk_mul_f32 v[60:61], v[60:61], v[196:197] op_sel_hi:[1,0]
	v_pk_mul_f32 v[62:63], v[62:63], v[196:197] op_sel_hi:[1,0]

; DI int tid_opaque() { int t = threadIdx.x; asm volatile("" : "+v"(t)); return t; }
; DI void dma_stage(const bf16_t* __restrict__ A, int lda, const bf16_t* __restrict__ B, int ldb, int k0, char* stage, int w, int lane) {
;   const int lr = lane >> 2, pos = lane & 3;
;   _Pragma("unroll") for (int i = 0; i < 4; ++i) {
;     const int idx = w + 8 * i;
;     const int row = (idx << 4) + lr;
;     const int c = pos ^ ((row >> 2) & 3);
;     const bf16_t* g = (i < 2) ? (A + (size_t)row * lda + k0 + c * 8) : (B + (size_t)(row - 256) * ldb + k0 + c * 8);
;     __builtin_amdgcn_global_load_lds((const unsigned*)g, (unsigned*)(stage + idx * 1024 + lane * 16), 16, 0, 0);
;   }
; }
; DI void gemm_mainloop(const bf16_t* __restrict__ A, int lda, const bf16_t* __restrict__ B, int ldb, int K,
;                       f32x16 (&acc)[2][4], char* smem, const int tid) {
;   const int lane = tid & 63, w = tid >> 6;
;   const int wm = w >> 1, wn = w & 1, r = lane & 31, h = lane >> 5;
;   const int swz = (r >> 2) & 3;
;   const int o0 = ((0 + h) ^ swz) << 4, o1 = ((2 + h) ^ swz) << 4;
;   const int aoff = (wm * 64 + r) * 64, boff = (256 + wn * 128 + r) * 64;
;   const int nk = K >> 5;
;   dma_stage(A, lda, B, ldb, 0, smem, w, lane);
;   dma_stage(A, lda, B, ldb, 32, smem + STG, w, lane);
;   dma_stage(A, lda, B, ldb, 64, smem + 2 * STG, w, lane);
; DI void p5_tile(const Params& P, int l, int half, int t, char* smem) {
;   int tm, tn; tile_decode(t, 8, tm, tn);
;   const int m0 = tm * 256, n0 = tn * 256;
;   const int tid = tid_opaque(), lane = tid & 63, w = tid >> 6, wm = w >> 1, wn = w & 1, r = lane & 31, h = lane >> 5;
;   f32x16 acc[2][4]; zero_acc(acc);
;   gemm_mainloop(P.merged + (size_t)m0 * 2048, 2048, P.wt_out + ((size_t)l * 2048 + n0) * 2048, 2048, 2048, acc, smem, tid);
.LBB0_751:
	s_ashr_i32 s0, s19, 31
	s_lshr_b32 s0, s0, 26
	s_add_i32 s0, s19, s0
	s_lshl_b32 s0, s0, 5
	v_mov_b32_e32 v157, v144
	s_and_b32 s22, s0, 0xfffff800
	s_lshl_b32 s0, s19, 8
	s_and_b32 s0, s0, 0x700
	v_ashrrev_i32_e32 v0, 1, v157
	s_lshl_b32 s1, s19, 5
	v_and_b32_e32 v156, 31, v157
	v_and_b32_e32 v155, 0xffffffc0, v0
	s_or_b32 s0, s22, s0
	s_sub_i32 s1, s1, s22
	v_ashrrev_i32_e32 v159, 6, v157
	v_or_b32_e32 v0, v155, v156
	s_and_b32 s14, s1, 0xffffff00
	s_ashr_i32 s1, s0, 31
	v_lshlrev_b32_e32 v161, 6, v0
	v_lshlrev_b32_e32 v0, 7, v159
	s_and_b32 s15, s18, 0x700
	s_lshl_b64 s[2:3], s[0:1], 12
	v_and_b32_e32 v160, 0x80, v0
	s_add_u32 s2, s60, s2
	v_or_b32_e32 v0, v160, v156
	v_and_b32_e32 v154, 63, v157
	s_addc_u32 s3, s61, s3
	s_ashr_i32 s1, s14, 31
	v_lshlrev_b32_e32 v162, 6, v0
	v_bfe_u32 v12, v157, 2, 4
	v_bfe_u32 v0, v157, 4, 2
	v_add_u32_e32 v13, 8, v159
	s_add_u32 s20, s14, s16
	v_bitop3_b32 v0, v0, v157, 3 bitop3:0x78
	v_lshlrev_b32_e32 v16, 4, v154
	v_lshl_or_b32 v4, v159, 4, v12
	v_lshl_or_b32 v10, v13, 4, v12
	s_addc_u32 s21, s1, 0
	v_add_u32_e32 v163, 0, v16
	v_lshlrev_b32_e32 v152, 4, v0
	v_ashrrev_i32_e32 v5, 31, v4
	v_lshlrev_b32_e32 v164, 10, v159
	v_ashrrev_i32_e32 v11, 31, v10
	s_lshl_b64 s[20:21], s[20:21], 12
	v_lshl_add_u64 v[2:3], s[2:3], 0, v[152:153]
	v_lshlrev_b64 v[6:7], 12, v[4:5]
	v_add_u32_e32 v5, v163, v164
	v_lshlrev_b64 v[10:11], 12, v[10:11]
	v_lshlrev_b32_e32 v165, 10, v13
	v_add_u32_e32 v13, 16, v159
	v_or_b32_e32 v12, 0xffffff00, v12
	s_add_u32 s20, s48, s20
	v_lshl_add_u64 v[8:9], v[2:3], 0, v[6:7]
	v_readfirstlane_b32 s1, v5
	v_lshl_add_u64 v[2:3], v[2:3], 0, v[10:11]
	v_add_u32_e32 v17, v163, v165
	v_lshl_add_u32 v10, v13, 4, v12
	v_lshlrev_b32_e32 v166, 10, v13
	v_add_u32_e32 v19, 24, v159
	s_addc_u32 s21, s49, s21
	s_mov_b32 m0, s1
	v_readfirstlane_b32 s1, v17
	v_ashrrev_i32_e32 v11, 31, v10
	v_add_u32_e32 v18, v163, v166
	v_lshl_add_u32 v12, v19, 4, v12
	v_lshlrev_b32_e32 v167, 10, v19
	v_lshl_add_u64 v[0:1], s[20:21], 0, v[152:153]
	global_load_lds_dwordx4 v[8:9], off
	s_mov_b32 m0, s1
	v_lshlrev_b64 v[10:11], 12, v[10:11]
	v_readfirstlane_b32 s1, v18
	v_ashrrev_i32_e32 v13, 31, v12
	v_add_u32_e32 v19, v163, v167
	global_load_lds_dwordx4 v[2:3], off
	v_lshl_add_u64 v[10:11], v[0:1], 0, v[10:11]
	s_mov_b32 m0, s1
	v_lshlrev_b64 v[12:13], 12, v[12:13]
	v_readfirstlane_b32 s1, v19
	v_add_u32_e32 v5, 0x8000, v5
	global_load_lds_dwordx4 v[10:11], off
	v_lshl_add_u64 v[0:1], v[0:1], 0, v[12:13]
	s_mov_b32 m0, s1
	v_readfirstlane_b32 s1, v5
	v_add_u32_e32 v5, 0x8000, v17
	global_load_lds_dwordx4 v[0:1], off
	v_lshl_add_u64 v[12:13], v[8:9], 0, 64
	s_mov_b32 m0, s1
	v_readfirstlane_b32 s1, v5
	v_add_u32_e32 v5, 0x8000, v18
	global_load_lds_dwordx4 v[12:13], off
	v_lshl_add_u64 v[12:13], v[2:3], 0, 64
	s_mov_b32 m0, s1
	v_readfirstlane_b32 s1, v5
	v_add_u32_e32 v5, 0x8000, v19
	global_load_lds_dwordx4 v[12:13], off
	v_lshl_add_u64 v[12:13], v[10:11], 0, 64
	s_mov_b32 m0, s1
	v_readfirstlane_b32 s1, v5
	global_load_lds_dwordx4 v[12:13], off
	s_mov_b32 m0, s1
	s_add_i32 s1, 0, 0x10000
	v_lshl_add_u64 v[12:13], v[0:1], 0, 64
	v_add_u32_e32 v5, s1, v16
	global_load_lds_dwordx4 v[12:13], off
	v_add_u32_e32 v12, v5, v164
	s_mov_b64 s[2:3], 0x80
	v_readfirstlane_b32 s1, v12
	v_lshl_add_u64 v[8:9], v[8:9], 0, s[2:3]
	s_mov_b32 m0, s1
	v_lshl_add_u64 v[2:3], v[2:3], 0, s[2:3]
	global_load_lds_dwordx4 v[8:9], off
	v_add_u32_e32 v8, v5, v165
	v_lshl_add_u64 v[0:1], v[0:1], 0, s[2:3]
	v_readfirstlane_b32 s1, v8
	v_add_u32_e32 v8, v5, v166
	s_mov_b32 m0, s1
	v_readfirstlane_b32 s1, v8
	global_load_lds_dwordx4 v[2:3], off
	v_lshl_add_u64 v[2:3], v[10:11], 0, s[2:3]
	s_mov_b32 m0, s1
	v_bfe_u32 v158, v157, 5, 1
	global_load_lds_dwordx4 v[2:3], off
	v_add_u32_e32 v2, v5, v167
	v_lshrrev_b32_e32 v14, 2, v157
	v_readfirstlane_b32 s1, v2
	s_mov_b32 m0, s1
	v_bfe_u32 v15, v157, 2, 2
	global_load_lds_dwordx4 v[0:1], off
	v_bitop3_b32 v0, v158, v14, 3 bitop3:0x78
	v_lshlrev_b32_e32 v168, 4, v0
	v_bitop3_b32 v0, v158, v15, 2 bitop3:0x36
	v_lshlrev_b32_e32 v169, 4, v0
	v_add_u32_e32 v0, 0x80, v4
	s_or_b32 s2, s22, s15
	v_ashrrev_i32_e32 v1, 31, v0
	s_ashr_i32 s3, s2, 31
	v_lshlrev_b64 v[0:1], 12, v[0:1]
	s_lshl_b64 s[2:3], s[2:3], 12
	v_lshl_add_u64 v[2:3], v[0:1], 0, s[2:3]
	s_sub_i32 s1, s17, s22
	v_or_b32_e32 v2, v2, v152
	s_and_b32 s1, s1, 0xffffff00
	v_lshl_add_u64 v[128:129], s[60:61], 0, v[2:3]
	v_lshl_add_u64 v[2:3], s[2:3], 0, v[6:7]
	s_ashr_i32 s3, s1, 31
	v_readlane_b32 s2, v247, 9
	s_add_u32 s2, s2, s1
	s_addc_u32 s3, 0, s3
	s_lshl_b64 s[2:3], s[2:3], 12
	v_lshl_add_u64 v[0:1], s[2:3], 0, v[0:1]
	v_or_b32_e32 v0, v0, v152
	v_lshl_add_u64 v[132:133], s[48:49], 0, v[0:1]
	v_lshl_add_u64 v[0:1], s[2:3], 0, v[6:7]
	v_or_b32_e32 v0, v0, v152
	v_or_b32_e32 v2, v2, v152
	v_lshl_add_u64 v[134:135], s[48:49], 0, v[0:1]
	v_mov_b32_e32 v0, 0
	v_lshl_add_u64 v[130:131], s[60:61], 0, v[2:3]
	s_mov_b64 s[2:3], 0
	s_mov_b32 s1, 0
	v_mov_b32_e32 v1, v0
	v_mov_b32_e32 v2, v0
	v_mov_b32_e32 v3, v0
	v_mov_b32_e32 v4, v0
	v_mov_b32_e32 v5, v0
	v_mov_b32_e32 v6, v0
	v_mov_b32_e32 v7, v0
	v_mov_b32_e32 v8, v0
	v_mov_b32_e32 v9, v0
	v_mov_b32_e32 v10, v0
	v_mov_b32_e32 v11, v0
	v_mov_b32_e32 v12, v0
	v_mov_b32_e32 v13, v0
	v_mov_b32_e32 v14, v0
	v_mov_b32_e32 v15, v0
	v_mov_b32_e32 v16, v0
	v_mov_b32_e32 v17, v0
	v_mov_b32_e32 v18, v0
	v_mov_b32_e32 v19, v0
	v_mov_b32_e32 v20, v0
	v_mov_b32_e32 v21, v0
	v_mov_b32_e32 v22, v0
	v_mov_b32_e32 v23, v0
	v_mov_b32_e32 v24, v0
	v_mov_b32_e32 v25, v0
	v_mov_b32_e32 v26, v0
	v_mov_b32_e32 v27, v0
	v_mov_b32_e32 v28, v0
	v_mov_b32_e32 v29, v0
	v_mov_b32_e32 v30, v0
	v_mov_b32_e32 v31, v0
; #define MFMA32(a, b, c) __builtin_amdgcn_mfma_f32_32x32x16_bf16((a), (b), (c), 0, 0, 0)
; DI void gemm_mainloop(const bf16_t* __restrict__ A, int lda, const bf16_t* __restrict__ B, int ldb, int K,
;                       f32x16 (&acc)[2][4], char* smem, const int tid) {
;     ...
;   dma_stage(A, lda, B, ldb, 0, smem, w, lane);
;   dma_stage(A, lda, B, ldb, 32, smem + STG, w, lane);
;   dma_stage(A, lda, B, ldb, 64, smem + 2 * STG, w, lane);
;   for (int kt = 0; kt < nk; ++kt) {
;     asm volatile("s_waitcnt vmcnt(8) lgkmcnt(0)" ::: "memory");
;     __builtin_amdgcn_s_barrier();
;     dma_stage(A, lda, B, ldb, (kt + 3) * 32, smem + ((kt + 3) & 3) * STG, w, lane);
;     const char* st = smem + (kt & 3) * STG;
;     _Pragma("unroll") for (int ks = 0; ks < 2; ++ks) {
;       const int oo = ks ? o1 : o0;
;       bf16x8 a0 = *(const bf16x8*)(st + aoff + oo);
;       bf16x8 a1 = *(const bf16x8*)(st + aoff + 32 * 64 + oo);
;       bf16x8 b0 = *(const bf16x8*)(st + boff + oo);
;       bf16x8 b1 = *(const bf16x8*)(st + boff + 32 * 64 + oo);
;       bf16x8 b2 = *(const bf16x8*)(st + boff + 64 * 64 + oo);
;       bf16x8 b3 = *(const bf16x8*)(st + boff + 96 * 64 + oo);
;       acc[0][0] = MFMA32(a0, b0, acc[0][0]); acc[0][1] = MFMA32(a0, b1, acc[0][1]);
;       acc[0][2] = MFMA32(a0, b2, acc[0][2]); acc[0][3] = MFMA32(a0, b3, acc[0][3]);
;       acc[1][0] = MFMA32(a1, b0, acc[1][0]); acc[1][1] = MFMA32(a1, b1, acc[1][1]);
;       acc[1][2] = MFMA32(a1, b2, acc[1][2]); acc[1][3] = MFMA32(a1, b3, acc[1][3]);
;     }
	v_mov_b32_e32 v64, v0
	v_mov_b32_e32 v65, v0
	v_mov_b32_e32 v66, v0
	v_mov_b32_e32 v67, v0
	v_mov_b32_e32 v68, v0
	v_mov_b32_e32 v69, v0
	v_mov_b32_e32 v70, v0
	v_mov_b32_e32 v71, v0
	v_mov_b32_e32 v72, v0
	v_mov_b32_e32 v73, v0
	v_mov_b32_e32 v74, v0
	v_mov_b32_e32 v75, v0
	v_mov_b32_e32 v76, v0
	v_mov_b32_e32 v77, v0
	v_mov_b32_e32 v78, v0
	v_mov_b32_e32 v79, v0
	v_mov_b32_e32 v80, v0
	v_mov_b32_e32 v81, v0
	v_mov_b32_e32 v82, v0
	v_mov_b32_e32 v83, v0
	v_mov_b32_e32 v84, v0
	v_mov_b32_e32 v85, v0
	v_mov_b32_e32 v86, v0
	v_mov_b32_e32 v87, v0
	v_mov_b32_e32 v88, v0
	v_mov_b32_e32 v89, v0
	v_mov_b32_e32 v90, v0
	v_mov_b32_e32 v91, v0
	v_mov_b32_e32 v92, v0
	v_mov_b32_e32 v93, v0
	v_mov_b32_e32 v94, v0
	v_mov_b32_e32 v95, v0
	v_mov_b32_e32 v32, v0
	v_mov_b32_e32 v33, v0
	v_mov_b32_e32 v34, v0
	v_mov_b32_e32 v35, v0
	v_mov_b32_e32 v36, v0
	v_mov_b32_e32 v37, v0
	v_mov_b32_e32 v38, v0
	v_mov_b32_e32 v39, v0
	v_mov_b32_e32 v40, v0
	v_mov_b32_e32 v41, v0
	v_mov_b32_e32 v42, v0
	v_mov_b32_e32 v43, v0
	v_mov_b32_e32 v44, v0
	v_mov_b32_e32 v45, v0
	v_mov_b32_e32 v46, v0
	v_mov_b32_e32 v47, v0
	v_mov_b32_e32 v48, v0
	v_mov_b32_e32 v49, v0
	v_mov_b32_e32 v50, v0
	v_mov_b32_e32 v51, v0
	v_mov_b32_e32 v52, v0
	v_mov_b32_e32 v53, v0
	v_mov_b32_e32 v54, v0
	v_mov_b32_e32 v55, v0
	v_mov_b32_e32 v56, v0
	v_mov_b32_e32 v57, v0
	v_mov_b32_e32 v58, v0
	v_mov_b32_e32 v59, v0
	v_mov_b32_e32 v60, v0
	v_mov_b32_e32 v61, v0
	v_mov_b32_e32 v62, v0
	v_mov_b32_e32 v63, v0
	v_mov_b32_e32 v96, v0
	v_mov_b32_e32 v97, v0
	v_mov_b32_e32 v98, v0
	v_mov_b32_e32 v99, v0
	v_mov_b32_e32 v100, v0
	v_mov_b32_e32 v101, v0
	v_mov_b32_e32 v102, v0
	v_mov_b32_e32 v103, v0
	v_mov_b32_e32 v104, v0
	v_mov_b32_e32 v105, v0
	v_mov_b32_e32 v106, v0
	v_mov_b32_e32 v107, v0
	v_mov_b32_e32 v108, v0
	v_mov_b32_e32 v109, v0
	v_mov_b32_e32 v110, v0
	v_mov_b32_e32 v111, v0
	v_mov_b32_e32 v112, v0
	v_mov_b32_e32 v113, v0
	v_mov_b32_e32 v114, v0
	v_mov_b32_e32 v115, v0
	v_mov_b32_e32 v116, v0
	v_mov_b32_e32 v117, v0
	v_mov_b32_e32 v118, v0
	v_mov_b32_e32 v119, v0
	v_mov_b32_e32 v120, v0
	v_mov_b32_e32 v121, v0
	v_mov_b32_e32 v122, v0
	v_mov_b32_e32 v123, v0
	v_mov_b32_e32 v124, v0
	v_mov_b32_e32 v125, v0
	v_mov_b32_e32 v126, v0
	v_mov_b32_e32 v127, v0
	s_mov_b64 s[24:25], 0xc0
	s_mov_b64 s[26:27], 0x100
	v_add_u32_e32 v205, v163, v164
	v_add_u32_e32 v195, v161, v168
	v_add_u32_e32 v196, v162, v168
	v_readfirstlane_b32 s15, v205
	v_add_u32_e32 v152, v161, v169
	v_add_u32_e32 v194, v162, v169
	s_waitcnt vmcnt(8) lgkmcnt(0)
	s_barrier
	ds_read_b128 v[170:173], v195
	ds_read_b128 v[174:177], v195 offset:2048
	ds_read_b128 v[178:181], v196 offset:16384
	ds_read_b128 v[182:185], v196 offset:18432
	ds_read_b128 v[186:189], v196 offset:20480
	ds_read_b128 v[190:193], v196 offset:22528
	ds_read_b128 v[212:215], v152
	ds_read_b128 v[216:219], v152 offset:2048
	ds_read_b128 v[220:223], v194 offset:16384
	ds_read_b128 v[224:227], v194 offset:18432
	ds_read_b128 v[228:231], v194 offset:20480
	ds_read_b128 v[232:235], v194 offset:22528
	s_add_u32 m0, s15, 0x18000
	v_lshl_add_u64 v[136:137], v[130:131], 0, s[24:25]
	v_lshl_add_u64 v[138:139], v[128:129], 0, s[24:25]
	global_load_lds_dwordx4 v[136:137], off
	s_add_u32 m0, s15, 0x1a000
	v_lshl_add_u64 v[136:137], v[134:135], 0, s[24:25]
	global_load_lds_dwordx4 v[138:139], off
	s_add_u32 m0, s15, 0x1c000
	v_lshl_add_u64 v[138:139], v[132:133], 0, s[24:25]
	global_load_lds_dwordx4 v[136:137], off
	s_add_u32 m0, s15, 0x1e000
	s_add_u32 s24, s24, 64
	global_load_lds_dwordx4 v[138:139], off
	s_addc_u32 s25, s25, 0
.Lgm_p5e_loop:
	s_waitcnt lgkmcnt(6)
	v_mfma_f32_32x32x16_bf16 v[112:127], v[170:173], v[178:181], v[112:127]
	v_mfma_f32_32x32x16_bf16 v[96:111], v[170:173], v[182:185], v[96:111]
	v_mfma_f32_32x32x16_bf16 v[48:63], v[170:173], v[186:189], v[48:63]
	v_mfma_f32_32x32x16_bf16 v[32:47], v[170:173], v[190:193], v[32:47]
	v_mfma_f32_32x32x16_bf16 v[80:95], v[174:177], v[178:181], v[80:95]
	v_mfma_f32_32x32x16_bf16 v[64:79], v[174:177], v[182:185], v[64:79]
	v_mfma_f32_32x32x16_bf16 v[16:31], v[174:177], v[186:189], v[16:31]
	v_mfma_f32_32x32x16_bf16 v[0:15], v[174:177], v[190:193], v[0:15]
	s_waitcnt vmcnt(8) lgkmcnt(0)
	s_barrier
	ds_read_b128 v[170:173], v195 offset:32768
	ds_read_b128 v[174:177], v195 offset:34816
	ds_read_b128 v[178:181], v196 offset:49152
	ds_read_b128 v[182:185], v196 offset:51200
	ds_read_b128 v[186:189], v196 offset:53248
	ds_read_b128 v[190:193], v196 offset:55296
	v_mfma_f32_32x32x16_bf16 v[112:127], v[212:215], v[220:223], v[112:127]
	s_mov_b32 m0, s15
	v_lshl_add_u64 v[136:137], v[130:131], 0, s[24:25]
	v_mfma_f32_32x32x16_bf16 v[96:111], v[212:215], v[224:227], v[96:111]
	global_load_lds_dwordx4 v[136:137], off
	s_add_u32 m0, s15, 0x2000
	v_lshl_add_u64 v[138:139], v[128:129], 0, s[24:25]
	v_mfma_f32_32x32x16_bf16 v[48:63], v[212:215], v[228:231], v[48:63]
	global_load_lds_dwordx4 v[138:139], off
	s_add_u32 m0, s15, 0x4000
	v_lshl_add_u64 v[136:137], v[134:135], 0, s[24:25]
	v_mfma_f32_32x32x16_bf16 v[32:47], v[212:215], v[232:235], v[32:47]
	global_load_lds_dwordx4 v[136:137], off
	s_add_u32 m0, s15, 0x6000
	v_lshl_add_u64 v[138:139], v[132:133], 0, s[24:25]
	v_mfma_f32_32x32x16_bf16 v[80:95], v[216:219], v[220:223], v[80:95]
	global_load_lds_dwordx4 v[138:139], off
	s_add_u32 s24, s24, 64
	s_addc_u32 s25, s25, 0
	v_mfma_f32_32x32x16_bf16 v[64:79], v[216:219], v[224:227], v[64:79]
	v_mfma_f32_32x32x16_bf16 v[16:31], v[216:219], v[228:231], v[16:31]
	v_mfma_f32_32x32x16_bf16 v[0:15], v[216:219], v[232:235], v[0:15]
	ds_read_b128 v[212:215], v152 offset:32768
	ds_read_b128 v[216:219], v152 offset:34816
	ds_read_b128 v[220:223], v194 offset:49152
	ds_read_b128 v[224:227], v194 offset:51200
	ds_read_b128 v[228:231], v194 offset:53248
	ds_read_b128 v[232:235], v194 offset:55296
	v_xor_b32_e32 v195, 0x10000, v195
	v_xor_b32_e32 v196, 0x10000, v196
	v_xor_b32_e32 v152, 0x10000, v152
	v_xor_b32_e32 v194, 0x10000, v194
	s_waitcnt lgkmcnt(6)
	v_mfma_f32_32x32x16_bf16 v[112:127], v[170:173], v[178:181], v[112:127]
	v_mfma_f32_32x32x16_bf16 v[96:111], v[170:173], v[182:185], v[96:111]
	v_mfma_f32_32x32x16_bf16 v[48:63], v[170:173], v[186:189], v[48:63]
	v_mfma_f32_32x32x16_bf16 v[32:47], v[170:173], v[190:193], v[32:47]
	v_mfma_f32_32x32x16_bf16 v[80:95], v[174:177], v[178:181], v[80:95]
	v_mfma_f32_32x32x16_bf16 v[64:79], v[174:177], v[182:185], v[64:79]
	v_mfma_f32_32x32x16_bf16 v[16:31], v[174:177], v[186:189], v[16:31]
	v_mfma_f32_32x32x16_bf16 v[0:15], v[174:177], v[190:193], v[0:15]
	s_waitcnt vmcnt(8) lgkmcnt(0)
	s_barrier
; DI void gemm_mainloop(const bf16_t* __restrict__ A, int lda, const bf16_t* __restrict__ B, int ldb, int K,
;                       f32x16 (&acc)[2][4], char* smem, const int tid) {
;     ...
;   for (int kt = 0; kt < nk; ++kt) {
;     asm volatile("s_waitcnt vmcnt(8) lgkmcnt(0)" ::: "memory");
;     __builtin_amdgcn_s_barrier();
;     dma_stage(A, lda, B, ldb, (kt + 3) * 32, smem + ((kt + 3) & 3) * STG, w, lane);
;     const char* st = smem + (kt & 3) * STG;
;     _Pragma("unroll") for (int ks = 0; ks < 2; ++ks) {
;       const int oo = ks ? o1 : o0;
;       bf16x8 a0 = *(const bf16x8*)(st + aoff + oo);
;       bf16x8 a1 = *(const bf16x8*)(st + aoff + 32 * 64 + oo);
;       bf16x8 b0 = *(const bf16x8*)(st + boff + oo);
;       bf16x8 b1 = *(const bf16x8*)(st + boff + 32 * 64 + oo);
;       bf16x8 b2 = *(const bf16x8*)(st + boff + 64 * 64 + oo);
;       bf16x8 b3 = *(const bf16x8*)(st + boff + 96 * 64 + oo);
;       acc[0][0] = MFMA32(a0, b0, acc[0][0]); acc[0][1] = MFMA32(a0, b1, acc[0][1]);
;       acc[0][2] = MFMA32(a0, b2, acc[0][2]); acc[0][3] = MFMA32(a0, b3, acc[0][3]);
;       acc[1][0] = MFMA32(a1, b0, acc[1][0]); acc[1][1] = MFMA32(a1, b1, acc[1][1]);
;       acc[1][2] = MFMA32(a1, b2, acc[1][2]); acc[1][3] = MFMA32(a1, b3, acc[1][3]);
;     }
;   }
;   asm volatile("s_waitcnt vmcnt(0)" ::: "memory");
;   __syncthreads();
; DI void p5_tile(const Params& P, int l, int half, int t, char* smem) {
;     ...
;   _Pragma("unroll") for (int seg = 0; seg < 2; ++seg) {
;     const int gc = n0 + wn * 128 + seg * 64 + ch * 8;
;     _Pragma("unroll") for (int mi = 0; mi < 2; ++mi) {
;       stage_block(acc[mi][2 * seg], acc[mi][2 * seg + 1], sE, r, h);
;       _Pragma("unroll") for (int ps = 0; ps < 4; ++ps) {
;         const int rr = ps * 8 + (lane >> 3);
;         const int m = m0 + wm * 64 + mi * 32 + rr;
;         const size_t off = (size_t)m * DM + gc;
;         float v[8]; read8(sE + rr * EST + ch * 8, v);
;         float x[8]; read8(xin + off, x);
;         _Pragma("unroll") for (int j = 0; j < 8; ++j) v[j] += x[j];
;         *(float4*)(xo + off) = make_float4(v[0], v[1], v[2], v[3]);
;         *(float4*)(xo + off + 4) = make_float4(v[4], v[5], v[6], v[7]);
;         if (l < DEPTH - 1) {
;           *(u32x4*)(xbo + off) = pack8u(v);
;           float sq = red8(sum8sq(v));
;           if (ch == 0) sqn[(size_t)m * 32 + ((n0 + wn * 128 + seg * 64) >> 6)] = sq;
;         }
	ds_read_b128 v[170:173], v195
	ds_read_b128 v[174:177], v195 offset:2048
	ds_read_b128 v[178:181], v196 offset:16384
	ds_read_b128 v[182:185], v196 offset:18432
	ds_read_b128 v[186:189], v196 offset:20480
	ds_read_b128 v[190:193], v196 offset:22528
	v_mfma_f32_32x32x16_bf16 v[112:127], v[212:215], v[220:223], v[112:127]
	s_add_u32 m0, s15, 0x8000
	v_lshl_add_u64 v[136:137], v[130:131], 0, s[24:25]
	v_mfma_f32_32x32x16_bf16 v[96:111], v[212:215], v[224:227], v[96:111]
	global_load_lds_dwordx4 v[136:137], off
	s_add_u32 m0, s15, 0xa000
	v_lshl_add_u64 v[138:139], v[128:129], 0, s[24:25]
	v_mfma_f32_32x32x16_bf16 v[48:63], v[212:215], v[228:231], v[48:63]
	global_load_lds_dwordx4 v[138:139], off
	s_add_u32 m0, s15, 0xc000
	v_lshl_add_u64 v[136:137], v[134:135], 0, s[24:25]
	v_mfma_f32_32x32x16_bf16 v[32:47], v[212:215], v[232:235], v[32:47]
	global_load_lds_dwordx4 v[136:137], off
	s_add_u32 m0, s15, 0xe000
	v_lshl_add_u64 v[138:139], v[132:133], 0, s[24:25]
	v_mfma_f32_32x32x16_bf16 v[80:95], v[216:219], v[220:223], v[80:95]
	global_load_lds_dwordx4 v[138:139], off
	s_add_u32 s24, s24, 64
	s_addc_u32 s25, s25, 0
	v_mfma_f32_32x32x16_bf16 v[64:79], v[216:219], v[224:227], v[64:79]
	v_mfma_f32_32x32x16_bf16 v[16:31], v[216:219], v[228:231], v[16:31]
	v_mfma_f32_32x32x16_bf16 v[0:15], v[216:219], v[232:235], v[0:15]
	ds_read_b128 v[212:215], v152
	ds_read_b128 v[216:219], v152 offset:2048
	ds_read_b128 v[220:223], v194 offset:16384
	ds_read_b128 v[224:227], v194 offset:18432
	ds_read_b128 v[228:231], v194 offset:20480
	ds_read_b128 v[232:235], v194 offset:22528
	s_xor_b32 s15, s15, 0x10000
	s_add_u32 s2, s2, 0x80
	s_cmpk_lg_i32 s2, 0x1000
	s_cbranch_scc1 .Lgm_p5e_loop
	s_waitcnt lgkmcnt(0)
	s_mov_b64 s[24:25], 0xc0
	s_movk_i32 s1, 0x2200
	v_mul_lo_u32 v128, v159, s1
	v_mul_u32_u24_e32 v129, 0x110, v158
	v_add_u32_e32 v130, 0, v128
	v_lshlrev_b32_e32 v129, 2, v129
	v_lshlrev_b32_e32 v132, 2, v156
	v_add3_u32 v134, v130, v129, v132
	v_add3_u32 v135, v130, v132, v129
	v_and_b32_e32 v131, 7, v157
	v_lshrrev_b32_e32 v129, 3, v154
	v_add_u32_e32 v143, s0, v155
	v_add_u32_e32 v136, 0x800, v134
	v_add_u32_e32 v137, 0x800, v135
	v_add_u32_e32 v140, 0x1000, v135
	s_waitcnt vmcnt(0)
	s_waitcnt vmcnt(0)
	s_barrier
	v_or_b32_e32 v128, s14, v160
	v_lshlrev_b32_e32 v152, 3, v131
	ds_write2_b32 v134, v112, v113 offset1:68
	ds_write2_b32 v135, v96, v97 offset0:32 offset1:100
	ds_write2_b32 v134, v114, v115 offset0:136 offset1:204
	ds_write2_b32 v135, v98, v99 offset0:168 offset1:236
	ds_write2_b32 v136, v116, v117 offset0:32 offset1:100
	ds_write2_b32 v137, v100, v101 offset0:64 offset1:132
	ds_write2_b32 v136, v118, v119 offset0:168 offset1:236
	ds_write2_b32 v140, v104, v105 offset0:96 offset1:164
	v_or_b32_e32 v104, v143, v129
	v_or_b32_e32 v132, v128, v152
	v_add_u32_e32 v141, 0x1200, v134
	v_ashrrev_i32_e32 v105, 31, v104
	v_ashrrev_i32_e32 v133, 31, v132
	ds_write2_b32 v141, v122, v123 offset0:72 offset1:140
	v_add_u32_e32 v123, 0x1200, v135
	v_add_u32_e32 v142, 0x1800, v134
	v_lshlrev_b64 v[112:113], 11, v[104:105]
	ds_write2_b32 v123, v106, v107 offset0:104 offset1:172
	ds_write2_b32 v142, v124, v125 offset0:96 offset1:164
	v_add_u32_e32 v125, 0x1a00, v134
	v_lshl_add_u64 v[106:107], v[112:113], 0, v[132:133]
	v_lshl_add_u32 v154, v131, 5, v130
	v_add_u32_e32 v138, 0xa00, v135
	v_add_u32_e32 v139, 0x1000, v134
	v_add_u32_e32 v124, 0x1800, v135
	ds_write2_b32 v125, v126, v127 offset0:104 offset1:172
	v_add_u32_e32 v126, 0x1c00, v135
	s_movk_i32 s2, 0x110
	v_lshlrev_b64 v[118:119], 2, v[106:107]
	ds_write2_b32 v138, v102, v103 offset0:72 offset1:140
	ds_write2_b32 v139, v120, v121 offset0:64 offset1:132
	ds_write2_b32 v124, v108, v109 offset0:128 offset1:196
	ds_write2_b32 v126, v110, v111 offset0:8 offset1:76
	v_mad_u32_u24 v102, v129, s2, v154
	v_lshl_add_u64 v[100:101], s[6:7], 0, v[118:119]
	ds_read_b128 v[96:99], v102
	ds_read_b128 v[108:111], v102 offset:16
	global_load_dwordx4 v[114:117], v[100:101], off offset:16
	s_nop 0
	global_load_dwordx4 v[100:103], v[100:101], off
	v_ashrrev_i32_e32 v130, 6, v128
	v_cmp_eq_u32_e64 s[0:1], 0, v131
	v_ashrrev_i32_e32 v131, 31, v130
	v_lshl_add_u64 v[130:131], v[130:131], 2, s[10:11]
	s_andn2_b64 vcc, exec, s[12:13]
	s_waitcnt vmcnt(0) lgkmcnt(1)
	v_pk_add_f32 v[100:101], v[96:97], v[100:101]
	v_pk_add_f32 v[102:103], v[98:99], v[102:103]
	s_waitcnt lgkmcnt(0)
	v_pk_add_f32 v[96:97], v[108:109], v[114:115]
	v_lshl_add_u64 v[108:109], s[4:5], 0, v[118:119]
	v_pk_add_f32 v[98:99], v[110:111], v[116:117]
	global_store_dwordx4 v[108:109], v[100:103], off
	global_store_dwordx4 v[108:109], v[96:99], off offset:16
	v_cndmask_b32_e64 v108, 0, 1, s[12:13]
	v_cmp_ne_u32_e64 s[2:3], 1, v108
	s_cbranch_vccnz .LBB0_757
	v_cvt_pk_bf16_f32 v108, v100, v101
	v_pk_mul_f32 v[100:101], v[100:101], v[100:101]
	v_cvt_pk_bf16_f32 v109, v102, v103
	v_pk_mul_f32 v[102:103], v[102:103], v[102:103]
	v_add_f32_e32 v100, v100, v101
	v_add_f32_e32 v100, v102, v100
	v_cvt_pk_bf16_f32 v110, v96, v97
	v_pk_mul_f32 v[96:97], v[96:97], v[96:97]
	v_add_f32_e32 v100, v103, v100
	v_add_f32_e32 v96, v96, v100
	v_add_f32_e32 v96, v97, v96
	v_xor_b32_e32 v97, 1, v145
	v_cvt_pk_bf16_f32 v111, v98, v99
	v_pk_mul_f32 v[98:99], v[98:99], v[98:99]
	v_cmp_lt_i32_e32 vcc, v97, v198
	v_add_f32_e32 v96, v98, v96
	v_add_f32_e32 v96, v99, v96
	v_cndmask_b32_e32 v97, v145, v97, vcc
	v_lshlrev_b32_e32 v97, 2, v97
	ds_bpermute_b32 v97, v97, v96
	v_lshl_add_u64 v[106:107], v[106:107], 1, s[8:9]
	global_store_dwordx4 v[106:107], v[108:111], off
	s_waitcnt lgkmcnt(0)
	v_add_f32_e32 v96, v96, v97
	v_xor_b32_e32 v97, 2, v145
	v_cmp_lt_i32_e32 vcc, v97, v198
	s_nop 1
	v_cndmask_b32_e32 v97, v145, v97, vcc
	v_lshlrev_b32_e32 v97, 2, v97
	ds_bpermute_b32 v97, v97, v96
	s_waitcnt lgkmcnt(0)
	v_add_f32_e32 v96, v96, v97
	v_xor_b32_e32 v97, 4, v145
	v_cmp_lt_i32_e32 vcc, v97, v198
	s_nop 1
	v_cndmask_b32_e32 v97, v145, v97, vcc
	v_lshlrev_b32_e32 v97, 2, v97
	ds_bpermute_b32 v97, v97, v96
	s_and_saveexec_b64 s[14:15], s[0:1]
	s_cbranch_execz .LBB0_756
	s_waitcnt lgkmcnt(0)
	v_add_f32_e32 v98, v96, v97
	v_lshlrev_b64 v[96:97], 7, v[104:105]
	v_lshl_add_u64 v[96:97], v[130:131], 0, v[96:97]
	global_store_dword v[96:97], v98, off
